# chained MFMA order + load segments without VALU copies + no s_setprio toggles in the K-loops
# speedup vs baseline: 1.0161x; 1.0064x over previous
; #define PG8_STAGE(bufoff, gbase, voff) do { const char* gb_ = (const char*)(gbase); asm volatile("" : "+s"(gb_)); _Pragma("unroll") for (int _i = 0; _i < 2; ++_i) { unsigned vo_ = (voff)[_i]; asm volatile("" : "+v"(vo_));        \
;         __builtin_amdgcn_global_load_lds((const unsigned*)(gb_ + vo_), (PG8_LAS unsigned*)(lds + (bufoff) + ldsw + _i * 8192), 16, 0, 0); } } while (0)
; #define PG8_LDA(dst, b, h) do { _Pragma("unroll") for (int m = 0; m < 4; ++m) _Pragma("unroll") for (int k = 0; k < 2; ++k) dst[m][k] = *(const PG8_LAS bf16x8*)(lds + PG8_SA(b, h) + aoff + m * 2048 + k * 1024); } while (0)
; #define PG8_LDB(dst, b, h) do { _Pragma("unroll") for (int n = 0; n < 2; ++n) _Pragma("unroll") for (int k = 0; k < 2; ++k) dst[n][k] = *(const PG8_LAS bf16x8*)(lds + PG8_SB(b, h) + boff + n * 2048 + k * 1024); } while (0)
; #define PG8_MMA(ai, bj, At, Bt) do { __builtin_amdgcn_s_setprio(1); _Pragma("unroll") for (int m = 0; m < 4; ++m) _Pragma("unroll") for (int n = 0; n < 2; ++n) _Pragma("unroll") for (int k = 0; k < 2; ++k) \
;         acc[ai][bj][m][n] = __builtin_amdgcn_mfma_f32_16x16x32_bf16(Bt[n][k], At[m][k], acc[ai][bj][m][n], 0, 0, 0); __builtin_amdgcn_s_setprio(0); } while (0)
; template <class Epi, class Sched, bool ALIGN_EPI = false, bool SP2 = false>
; __device__ __forceinline__ void gemm_phase(PG8_LAS unsigned char* lds, const Gemm g, const Sched& S, const Epi& E) {
;     ...
;         for (int t = 0; t < nt; t += 2) {
;             const bool last = (t == nt - 2);
;             const char* a1 = cA + (size_t)(t + 1) * kstep;
;             const char* a2 = last ? nA : cA + (size_t)(t + 2) * kstep; const char* b2 = last ? nB : cB + (size_t)(t + 2) * kstep;
;             const char* a3 = a2 + kstep; const char* b3 = b2 + kstep;
;             if (last && has_next) S.a_ready(nxt);
;             if constexpr (SP2) {
;             PG8_LDB(B0, 0, 0); PG8_LDB(B1, 0, 1); PG8_SCHED; PG8_LDA(At, 0, 0); PG8_STAGE(PG8_SA(1, 1), a1 + hstep, voffA);
;             PG8_WAIT_V(8); PG8_WAIT_L(0); PG8_BAR; PG8_MMA(0, 0, At, B0); PG8_MMA(0, 1, At, B1); PG8_BAR; PG8_SCHED;
;             PG8_LDA(At, 0, 1); PG8_STAGE(PG8_SB(0, 0), b2, voffB); PG8_STAGE(PG8_SB(0, 1), b2 + hstep, voffB); PG8_STAGE(PG8_SA(0, 0), a2, voffA);
;             PG8_WAIT_V(8); PG8_WAIT_L(0); PG8_BAR; PG8_MMA(1, 0, At, B0); PG8_MMA(1, 1, At, B1); PG8_BAR; PG8_SCHED;
.LBB0_232:
	s_add_u32 s2, s0, 0x100
	s_addc_u32 s3, s1, 0
	s_cmp_eq_u32 s30, 28
	s_cselect_b32 s10, s25, s2
	s_cselect_b32 s11, s24, s3
	s_cselect_b32 s8, s27, s28
	s_cselect_b32 s9, s26, s29
	s_add_u32 s6, s10, 0x80
	s_addc_u32 s7, s11, 0
	s_add_i32 s31, 0, 0x10000
	s_add_i32 s33, 0, 0x14000
	ds_read_b128 v[66:69], v244
	ds_read_b128 v[70:73], v244 offset:1024
	ds_read_b128 v[74:77], v244 offset:2048
	ds_read_b128 v[78:81], v244 offset:3072
	ds_read_b128 v[146:149], v244 offset:16384
	ds_read_b128 v[150:153], v244 offset:17408
	ds_read_b128 v[154:157], v244 offset:18432
	ds_read_b128 v[158:161], v244 offset:19456
	s_add_u32 s0, s0, 0x80080
	s_addc_u32 s1, s1, 0
	ds_read_b128 v[178:181], v223
	ds_read_b128 v[182:185], v223 offset:1024
	ds_read_b128 v[192:195], v223 offset:2048
	ds_read_b128 v[196:199], v223 offset:3072
	ds_read_b128 v[200:203], v223 offset:4096
	ds_read_b128 v[204:207], v223 offset:5120
	ds_read_b128 v[208:211], v223 offset:6144
	ds_read_b128 v[212:215], v223 offset:7168
	s_add_i32 m0, s13, 0xc000
	s_nop 0
	global_load_lds_dwordx4 v1, s[0:1]
	s_add_i32 m0, s13, 0xe000
	s_nop 0
	global_load_lds_dwordx4 v191, s[0:1]
	s_waitcnt vmcnt(8)
	s_waitcnt lgkmcnt(0)
	s_barrier
	s_waitcnt lgkmcnt(0)
	v_mfma_f32_16x16x32_bf16 v[142:145], v[66:69], v[178:181], v[142:145]
	v_mfma_f32_16x16x32_bf16 v[142:145], v[70:73], v[182:185], v[142:145]
	v_mfma_f32_16x16x32_bf16 v[134:137], v[66:69], v[192:195], v[134:137]
	v_mfma_f32_16x16x32_bf16 v[134:137], v[70:73], v[196:199], v[134:137]
	v_mfma_f32_16x16x32_bf16 v[126:129], v[66:69], v[200:203], v[126:129]
	v_mfma_f32_16x16x32_bf16 v[126:129], v[70:73], v[204:207], v[126:129]
	v_mfma_f32_16x16x32_bf16 v[118:121], v[66:69], v[208:211], v[118:121]
	v_mfma_f32_16x16x32_bf16 v[118:121], v[70:73], v[212:215], v[118:121]
	v_mfma_f32_16x16x32_bf16 v[138:141], v[74:77], v[178:181], v[138:141]
	v_mfma_f32_16x16x32_bf16 v[138:141], v[78:81], v[182:185], v[138:141]
	v_mfma_f32_16x16x32_bf16 v[130:133], v[74:77], v[192:195], v[130:133]
	v_mfma_f32_16x16x32_bf16 v[130:133], v[78:81], v[196:199], v[130:133]
	v_mfma_f32_16x16x32_bf16 v[122:125], v[74:77], v[200:203], v[122:125]
	v_mfma_f32_16x16x32_bf16 v[122:125], v[78:81], v[204:207], v[122:125]
	v_mfma_f32_16x16x32_bf16 v[114:117], v[74:77], v[208:211], v[114:117]
	v_mfma_f32_16x16x32_bf16 v[114:117], v[78:81], v[212:215], v[114:117]
	v_mfma_f32_16x16x32_bf16 v[62:65], v[146:149], v[178:181], v[62:65]
	v_mfma_f32_16x16x32_bf16 v[62:65], v[150:153], v[182:185], v[62:65]
	v_mfma_f32_16x16x32_bf16 v[54:57], v[146:149], v[192:195], v[54:57]
	v_mfma_f32_16x16x32_bf16 v[54:57], v[150:153], v[196:199], v[54:57]
	v_mfma_f32_16x16x32_bf16 v[46:49], v[146:149], v[200:203], v[46:49]
	v_mfma_f32_16x16x32_bf16 v[46:49], v[150:153], v[204:207], v[46:49]
	v_mfma_f32_16x16x32_bf16 v[38:41], v[146:149], v[208:211], v[38:41]
	v_mfma_f32_16x16x32_bf16 v[38:41], v[150:153], v[212:215], v[38:41]
	v_mfma_f32_16x16x32_bf16 v[58:61], v[154:157], v[178:181], v[58:61]
	v_mfma_f32_16x16x32_bf16 v[58:61], v[158:161], v[182:185], v[58:61]
	v_mfma_f32_16x16x32_bf16 v[50:53], v[154:157], v[192:195], v[50:53]
	v_mfma_f32_16x16x32_bf16 v[50:53], v[158:161], v[196:199], v[50:53]
	v_mfma_f32_16x16x32_bf16 v[42:45], v[154:157], v[200:203], v[42:45]
	v_mfma_f32_16x16x32_bf16 v[42:45], v[158:161], v[204:207], v[42:45]
	v_mfma_f32_16x16x32_bf16 v[34:37], v[154:157], v[208:211], v[34:37]
	v_mfma_f32_16x16x32_bf16 v[34:37], v[158:161], v[212:215], v[34:37]
	s_barrier
	s_mov_b64 s[0:1], s[8:9]
	s_add_i32 s31, s31, s12
	ds_read_b128 v[178:181], v223 offset:16384
	ds_read_b128 v[182:185], v223 offset:17408
	ds_read_b128 v[192:195], v223 offset:18432
	ds_read_b128 v[196:199], v223 offset:19456
	ds_read_b128 v[200:203], v223 offset:20480
	ds_read_b128 v[204:207], v223 offset:21504
	ds_read_b128 v[208:211], v223 offset:22528
	ds_read_b128 v[212:215], v223 offset:23552
	s_mov_b32 m0, s31
	s_nop 0
	global_load_lds_dwordx4 v189, s[0:1]
	s_add_i32 m0, s31, 0x2000
	s_nop 0
	global_load_lds_dwordx4 v219, s[0:1]
	s_add_u32 s0, s8, 0x80000
	s_addc_u32 s1, s9, 0
	s_add_i32 s31, s33, s12
	s_mov_b32 m0, s31
	s_nop 0
	global_load_lds_dwordx4 v189, s[0:1]
	s_add_i32 m0, s31, 0x2000
	s_nop 0
	global_load_lds_dwordx4 v219, s[0:1]
	s_mov_b64 s[0:1], s[10:11]
	s_mov_b32 m0, s13
	s_nop 0
	global_load_lds_dwordx4 v1, s[0:1]
	s_mov_b32 m0, s14
	s_nop 0
	global_load_lds_dwordx4 v191, s[0:1]
	s_waitcnt vmcnt(8)
	s_waitcnt lgkmcnt(0)
	s_barrier
	s_waitcnt lgkmcnt(0)
	v_mfma_f32_16x16x32_bf16 v[110:113], v[66:69], v[178:181], v[110:113]
	v_mfma_f32_16x16x32_bf16 v[110:113], v[70:73], v[182:185], v[110:113]
	v_mfma_f32_16x16x32_bf16 v[102:105], v[66:69], v[192:195], v[102:105]
	v_mfma_f32_16x16x32_bf16 v[102:105], v[70:73], v[196:199], v[102:105]
	v_mfma_f32_16x16x32_bf16 v[94:97], v[66:69], v[200:203], v[94:97]
	v_mfma_f32_16x16x32_bf16 v[94:97], v[70:73], v[204:207], v[94:97]
	v_mfma_f32_16x16x32_bf16 v[66:69], v[66:69], v[208:211], v[86:89]
	v_mfma_f32_16x16x32_bf16 v[66:69], v[70:73], v[212:215], v[66:69]
	v_mfma_f32_16x16x32_bf16 v[106:109], v[74:77], v[178:181], v[106:109]
	v_mfma_f32_16x16x32_bf16 v[106:109], v[78:81], v[182:185], v[106:109]
	v_mfma_f32_16x16x32_bf16 v[98:101], v[74:77], v[192:195], v[98:101]
	v_mfma_f32_16x16x32_bf16 v[98:101], v[78:81], v[196:199], v[98:101]
	v_mfma_f32_16x16x32_bf16 v[90:93], v[74:77], v[200:203], v[90:93]
	v_mfma_f32_16x16x32_bf16 v[90:93], v[78:81], v[204:207], v[90:93]
	v_mfma_f32_16x16x32_bf16 v[70:73], v[74:77], v[208:211], v[82:85]
	v_mfma_f32_16x16x32_bf16 v[70:73], v[78:81], v[212:215], v[70:73]
	v_mfma_f32_16x16x32_bf16 v[30:33], v[146:149], v[178:181], v[30:33]
	v_mfma_f32_16x16x32_bf16 v[30:33], v[150:153], v[182:185], v[30:33]
	v_mfma_f32_16x16x32_bf16 v[22:25], v[146:149], v[192:195], v[22:25]
	v_mfma_f32_16x16x32_bf16 v[22:25], v[150:153], v[196:199], v[22:25]
	v_mfma_f32_16x16x32_bf16 v[14:17], v[146:149], v[200:203], v[14:17]
	v_mfma_f32_16x16x32_bf16 v[14:17], v[150:153], v[204:207], v[14:17]
	v_mfma_f32_16x16x32_bf16 v[6:9], v[146:149], v[208:211], v[6:9]
	v_mfma_f32_16x16x32_bf16 v[6:9], v[150:153], v[212:215], v[6:9]
	v_mfma_f32_16x16x32_bf16 v[26:29], v[154:157], v[178:181], v[26:29]
	v_mfma_f32_16x16x32_bf16 v[26:29], v[158:161], v[182:185], v[26:29]
	v_mfma_f32_16x16x32_bf16 v[18:21], v[154:157], v[192:195], v[18:21]
	v_mfma_f32_16x16x32_bf16 v[18:21], v[158:161], v[196:199], v[18:21]
	v_mfma_f32_16x16x32_bf16 v[10:13], v[154:157], v[200:203], v[10:13]
	v_mfma_f32_16x16x32_bf16 v[10:13], v[158:161], v[204:207], v[10:13]
	v_mfma_f32_16x16x32_bf16 v[2:5], v[154:157], v[208:211], v[2:5]
	v_mfma_f32_16x16x32_bf16 v[2:5], v[158:161], v[212:215], v[2:5]
	s_barrier
; #define PG8_STAGE(bufoff, gbase, voff) do { const char* gb_ = (const char*)(gbase); asm volatile("" : "+s"(gb_)); _Pragma("unroll") for (int _i = 0; _i < 2; ++_i) { unsigned vo_ = (voff)[_i]; asm volatile("" : "+v"(vo_));        \
;         __builtin_amdgcn_global_load_lds((const unsigned*)(gb_ + vo_), (PG8_LAS unsigned*)(lds + (bufoff) + ldsw + _i * 8192), 16, 0, 0); } } while (0)
; #define PG8_LDA(dst, b, h) do { _Pragma("unroll") for (int m = 0; m < 4; ++m) _Pragma("unroll") for (int k = 0; k < 2; ++k) dst[m][k] = *(const PG8_LAS bf16x8*)(lds + PG8_SA(b, h) + aoff + m * 2048 + k * 1024); } while (0)
; #define PG8_LDB(dst, b, h) do { _Pragma("unroll") for (int n = 0; n < 2; ++n) _Pragma("unroll") for (int k = 0; k < 2; ++k) dst[n][k] = *(const PG8_LAS bf16x8*)(lds + PG8_SB(b, h) + boff + n * 2048 + k * 1024); } while (0)
; #define PG8_MMA(ai, bj, At, Bt) do { __builtin_amdgcn_s_setprio(1); _Pragma("unroll") for (int m = 0; m < 4; ++m) _Pragma("unroll") for (int n = 0; n < 2; ++n) _Pragma("unroll") for (int k = 0; k < 2; ++k) \
;         acc[ai][bj][m][n] = __builtin_amdgcn_mfma_f32_16x16x32_bf16(Bt[n][k], At[m][k], acc[ai][bj][m][n], 0, 0, 0); __builtin_amdgcn_s_setprio(0); } while (0)
; #define PG8_WAIT_V(n) asm volatile("s_waitcnt vmcnt(" #n ")" ::: "memory")
; #define PG8_WAIT_L(n) asm volatile("s_waitcnt lgkmcnt(" #n ")" ::: "memory")
; #define PG8_BAR __builtin_amdgcn_s_barrier()
; #define PG8_SCHED __builtin_amdgcn_sched_barrier(0)
; template <class Epi, class Sched, bool ALIGN_EPI = false, bool SP2 = false>
; __device__ __forceinline__ void gemm_phase(PG8_LAS unsigned char* lds, const Gemm g, const Sched& S, const Epi& E) {
;     ...
;             PG8_LDB(B0, 1, 0); PG8_LDB(B1, 1, 1); PG8_SCHED; PG8_LDA(At, 1, 0); PG8_STAGE(PG8_SA(0, 1), a2 + hstep, voffA);
;             PG8_WAIT_V(8); PG8_WAIT_L(0); PG8_BAR; PG8_MMA(0, 0, At, B0); PG8_MMA(0, 1, At, B1); PG8_BAR; PG8_SCHED;
;             PG8_LDA(At, 1, 1); PG8_STAGE(PG8_SB(1, 0), b3, voffB); PG8_STAGE(PG8_SB(1, 1), b3 + hstep, voffB); PG8_STAGE(PG8_SA(1, 0), a3, voffA);
;             PG8_WAIT_V(8); PG8_WAIT_L(0); PG8_BAR; PG8_MMA(1, 0, At, B0); PG8_MMA(1, 1, At, B1); PG8_BAR; PG8_SCHED;
;     ...
;         if constexpr (ALIGN_EPI) { if (wr == 0) PG8_BAR; }
	s_add_i32 s31, 0, 0x18000
	s_add_i32 s33, 0, 0x1c000
	ds_read_b128 v[74:77], v244 offset:32768
	ds_read_b128 v[78:81], v244 offset:33792
	ds_read_b128 v[82:85], v244 offset:34816
	ds_read_b128 v[146:149], v244 offset:35840
	ds_read_b128 v[150:153], v244 offset:49152
	ds_read_b128 v[154:157], v244 offset:50176
	ds_read_b128 v[158:161], v244 offset:51200
	ds_read_b128 v[178:181], v244 offset:52224
	s_add_u32 s0, s10, 0x80000
	s_addc_u32 s1, s11, 0
	s_mov_b32 m0, s15
	ds_read_b128 v[86:89], v223 offset:32768
	ds_read_b128 v[182:185], v223 offset:33792
	ds_read_b128 v[192:195], v223 offset:34816
	ds_read_b128 v[196:199], v223 offset:35840
	ds_read_b128 v[200:203], v223 offset:36864
	ds_read_b128 v[204:207], v223 offset:37888
	ds_read_b128 v[208:211], v223 offset:38912
	ds_read_b128 v[212:215], v223 offset:39936
	s_nop 0
	global_load_lds_dwordx4 v1, s[0:1]
	s_mov_b32 m0, s16
	s_nop 0
	global_load_lds_dwordx4 v191, s[0:1]
	s_waitcnt vmcnt(8)
	s_waitcnt lgkmcnt(0)
	s_barrier
	s_waitcnt lgkmcnt(0)
	v_mfma_f32_16x16x32_bf16 v[142:145], v[74:77], v[86:89], v[142:145]
	v_mfma_f32_16x16x32_bf16 v[142:145], v[78:81], v[182:185], v[142:145]
	v_mfma_f32_16x16x32_bf16 v[134:137], v[74:77], v[192:195], v[134:137]
	v_mfma_f32_16x16x32_bf16 v[134:137], v[78:81], v[196:199], v[134:137]
	v_mfma_f32_16x16x32_bf16 v[126:129], v[74:77], v[200:203], v[126:129]
	v_mfma_f32_16x16x32_bf16 v[126:129], v[78:81], v[204:207], v[126:129]
	v_mfma_f32_16x16x32_bf16 v[118:121], v[74:77], v[208:211], v[118:121]
	v_mfma_f32_16x16x32_bf16 v[118:121], v[78:81], v[212:215], v[118:121]
	v_mfma_f32_16x16x32_bf16 v[138:141], v[82:85], v[86:89], v[138:141]
	v_mfma_f32_16x16x32_bf16 v[138:141], v[146:149], v[182:185], v[138:141]
	v_mfma_f32_16x16x32_bf16 v[130:133], v[82:85], v[192:195], v[130:133]
	v_mfma_f32_16x16x32_bf16 v[130:133], v[146:149], v[196:199], v[130:133]
	v_mfma_f32_16x16x32_bf16 v[122:125], v[82:85], v[200:203], v[122:125]
	v_mfma_f32_16x16x32_bf16 v[122:125], v[146:149], v[204:207], v[122:125]
	v_mfma_f32_16x16x32_bf16 v[114:117], v[82:85], v[208:211], v[114:117]
	v_mfma_f32_16x16x32_bf16 v[114:117], v[146:149], v[212:215], v[114:117]
	v_mfma_f32_16x16x32_bf16 v[62:65], v[150:153], v[86:89], v[62:65]
	v_mfma_f32_16x16x32_bf16 v[62:65], v[154:157], v[182:185], v[62:65]
	v_mfma_f32_16x16x32_bf16 v[54:57], v[150:153], v[192:195], v[54:57]
	v_mfma_f32_16x16x32_bf16 v[54:57], v[154:157], v[196:199], v[54:57]
	v_mfma_f32_16x16x32_bf16 v[46:49], v[150:153], v[200:203], v[46:49]
	v_mfma_f32_16x16x32_bf16 v[46:49], v[154:157], v[204:207], v[46:49]
	v_mfma_f32_16x16x32_bf16 v[38:41], v[150:153], v[208:211], v[38:41]
	v_mfma_f32_16x16x32_bf16 v[38:41], v[154:157], v[212:215], v[38:41]
	v_mfma_f32_16x16x32_bf16 v[58:61], v[158:161], v[86:89], v[58:61]
	v_mfma_f32_16x16x32_bf16 v[58:61], v[178:181], v[182:185], v[58:61]
	v_mfma_f32_16x16x32_bf16 v[50:53], v[158:161], v[192:195], v[50:53]
	v_mfma_f32_16x16x32_bf16 v[50:53], v[178:181], v[196:199], v[50:53]
	v_mfma_f32_16x16x32_bf16 v[42:45], v[158:161], v[200:203], v[42:45]
	v_mfma_f32_16x16x32_bf16 v[42:45], v[178:181], v[204:207], v[42:45]
	v_mfma_f32_16x16x32_bf16 v[34:37], v[158:161], v[208:211], v[34:37]
	v_mfma_f32_16x16x32_bf16 v[34:37], v[178:181], v[212:215], v[34:37]
	s_barrier
	s_add_u32 s0, s8, 0x80
	s_addc_u32 s1, s9, 0
	s_add_i32 s10, s31, s12
	ds_read_b128 v[182:185], v223 offset:49152
	ds_read_b128 v[192:195], v223 offset:50176
	ds_read_b128 v[196:199], v223 offset:51200
	ds_read_b128 v[200:203], v223 offset:52224
	ds_read_b128 v[204:207], v223 offset:53248
	ds_read_b128 v[208:211], v223 offset:54272
	ds_read_b128 v[212:215], v223 offset:55296
	ds_read_b128 v[224:227], v223 offset:56320
	s_mov_b32 m0, s10
	s_nop 0
	global_load_lds_dwordx4 v189, s[0:1]
	s_add_i32 m0, s10, 0x2000
	s_nop 0
	global_load_lds_dwordx4 v219, s[0:1]
	s_add_u32 s0, s8, 0x80080
	s_addc_u32 s1, s9, 0
	s_add_i32 s8, s33, s12
	s_mov_b32 m0, s8
	s_nop 0
	global_load_lds_dwordx4 v189, s[0:1]
	s_add_i32 m0, s8, 0x2000
	s_nop 0
	global_load_lds_dwordx4 v219, s[0:1]
	s_mov_b32 m0, s19
	s_nop 0
	global_load_lds_dwordx4 v1, s[6:7]
	s_mov_b32 m0, s20
	s_nop 0
	global_load_lds_dwordx4 v191, s[6:7]
	s_waitcnt vmcnt(8)
	s_waitcnt lgkmcnt(0)
	s_barrier
	s_waitcnt lgkmcnt(0)
	v_mfma_f32_16x16x32_bf16 v[86:89], v[74:77], v[182:185], v[110:113]
	v_mfma_f32_16x16x32_bf16 v[110:113], v[78:81], v[192:195], v[86:89]
	v_mfma_f32_16x16x32_bf16 v[66:69], v[74:77], v[212:215], v[66:69]
	v_mfma_f32_16x16x32_bf16 v[86:89], v[82:85], v[182:185], v[106:109]
	v_mfma_f32_16x16x32_bf16 v[106:109], v[146:149], v[192:195], v[86:89]
	v_mfma_f32_16x16x32_bf16 v[86:89], v[74:77], v[196:199], v[102:105]
	v_mfma_f32_16x16x32_bf16 v[102:105], v[78:81], v[200:203], v[86:89]
	v_mfma_f32_16x16x32_bf16 v[86:89], v[82:85], v[196:199], v[98:101]
	v_mfma_f32_16x16x32_bf16 v[98:101], v[146:149], v[200:203], v[86:89]
	v_mfma_f32_16x16x32_bf16 v[86:89], v[74:77], v[204:207], v[94:97]
	v_mfma_f32_16x16x32_bf16 v[94:97], v[78:81], v[208:211], v[86:89]
	v_mfma_f32_16x16x32_bf16 v[86:89], v[82:85], v[204:207], v[90:93]
	v_mfma_f32_16x16x32_bf16 v[90:93], v[146:149], v[208:211], v[86:89]
	v_mfma_f32_16x16x32_bf16 v[86:89], v[78:81], v[224:227], v[66:69]
	v_mfma_f32_16x16x32_bf16 v[66:69], v[82:85], v[212:215], v[70:73]
	v_mfma_f32_16x16x32_bf16 v[82:85], v[146:149], v[224:227], v[66:69]
	v_mfma_f32_16x16x32_bf16 v[30:33], v[150:153], v[182:185], v[30:33]
	v_mfma_f32_16x16x32_bf16 v[30:33], v[154:157], v[192:195], v[30:33]
	v_mfma_f32_16x16x32_bf16 v[22:25], v[150:153], v[196:199], v[22:25]
	v_mfma_f32_16x16x32_bf16 v[22:25], v[154:157], v[200:203], v[22:25]
	v_mfma_f32_16x16x32_bf16 v[14:17], v[150:153], v[204:207], v[14:17]
	v_mfma_f32_16x16x32_bf16 v[14:17], v[154:157], v[208:211], v[14:17]
	v_mfma_f32_16x16x32_bf16 v[6:9], v[150:153], v[212:215], v[6:9]
	v_mfma_f32_16x16x32_bf16 v[6:9], v[154:157], v[224:227], v[6:9]
	v_mfma_f32_16x16x32_bf16 v[26:29], v[158:161], v[182:185], v[26:29]
	v_mfma_f32_16x16x32_bf16 v[26:29], v[178:181], v[192:195], v[26:29]
	v_mfma_f32_16x16x32_bf16 v[18:21], v[158:161], v[196:199], v[18:21]
	v_mfma_f32_16x16x32_bf16 v[18:21], v[178:181], v[200:203], v[18:21]
	v_mfma_f32_16x16x32_bf16 v[10:13], v[158:161], v[204:207], v[10:13]
	v_mfma_f32_16x16x32_bf16 v[10:13], v[178:181], v[208:211], v[10:13]
	v_mfma_f32_16x16x32_bf16 v[2:5], v[158:161], v[212:215], v[2:5]
	v_mfma_f32_16x16x32_bf16 v[2:5], v[178:181], v[224:227], v[2:5]
	s_barrier
	s_add_i32 s30, s30, 2
	s_add_u32 s28, s28, 0x100
	s_addc_u32 s29, s29, 0
	s_cmp_gt_u32 s30, 29
	s_mov_b64 s[0:1], s[2:3]
	s_cbranch_scc0 .LBB0_232
	s_and_b64 vcc, exec, s[44:45]
	s_cbranch_vccz .LBB0_235
	s_barrier

; #define PG8_STAGE(bufoff, gbase, voff) do { const char* gb_ = (const char*)(gbase); asm volatile("" : "+s"(gb_)); _Pragma("unroll") for (int _i = 0; _i < 2; ++_i) { unsigned vo_ = (voff)[_i]; asm volatile("" : "+v"(vo_));        \
;         __builtin_amdgcn_global_load_lds((const unsigned*)(gb_ + vo_), (PG8_LAS unsigned*)(lds + (bufoff) + ldsw + _i * 8192), 16, 0, 0); } } while (0)
; #define PG8_LDA(dst, b, h) do { _Pragma("unroll") for (int m = 0; m < 4; ++m) _Pragma("unroll") for (int k = 0; k < 2; ++k) dst[m][k] = *(const PG8_LAS bf16x8*)(lds + PG8_SA(b, h) + aoff + m * 2048 + k * 1024); } while (0)
; #define PG8_LDB(dst, b, h) do { _Pragma("unroll") for (int n = 0; n < 2; ++n) _Pragma("unroll") for (int k = 0; k < 2; ++k) dst[n][k] = *(const PG8_LAS bf16x8*)(lds + PG8_SB(b, h) + boff + n * 2048 + k * 1024); } while (0)
; #define PG8_MMA(ai, bj, At, Bt) do { __builtin_amdgcn_s_setprio(1); _Pragma("unroll") for (int m = 0; m < 4; ++m) _Pragma("unroll") for (int n = 0; n < 2; ++n) _Pragma("unroll") for (int k = 0; k < 2; ++k) \
;         acc[ai][bj][m][n] = __builtin_amdgcn_mfma_f32_16x16x32_bf16(Bt[n][k], At[m][k], acc[ai][bj][m][n], 0, 0, 0); __builtin_amdgcn_s_setprio(0); } while (0)
; template <class Epi, class Sched, bool ALIGN_EPI = false, bool SP2 = false>
; __device__ __forceinline__ void gemm_phase(PG8_LAS unsigned char* lds, const Gemm g, const Sched& S, const Epi& E) {
;     ...
;         for (int t = 0; t < nt; t += 2) {
;             const bool last = (t == nt - 2);
;             const char* a1 = cA + (size_t)(t + 1) * kstep;
;             const char* a2 = last ? nA : cA + (size_t)(t + 2) * kstep; const char* b2 = last ? nB : cB + (size_t)(t + 2) * kstep;
;             const char* a3 = a2 + kstep; const char* b3 = b2 + kstep;
;             if (last && has_next) S.a_ready(nxt);
;             if constexpr (SP2) {
;             PG8_LDB(B0, 0, 0); PG8_LDB(B1, 0, 1); PG8_SCHED; PG8_LDA(At, 0, 0); PG8_STAGE(PG8_SA(1, 1), a1 + hstep, voffA);
;             PG8_WAIT_V(8); PG8_WAIT_L(0); PG8_BAR; PG8_MMA(0, 0, At, B0); PG8_MMA(0, 1, At, B1); PG8_BAR; PG8_SCHED;
;             PG8_LDA(At, 0, 1); PG8_STAGE(PG8_SB(0, 0), b2, voffB); PG8_STAGE(PG8_SB(0, 1), b2 + hstep, voffB); PG8_STAGE(PG8_SA(0, 0), a2, voffA);
;             PG8_WAIT_V(8); PG8_WAIT_L(0); PG8_BAR; PG8_MMA(1, 0, At, B0); PG8_MMA(1, 1, At, B1); PG8_BAR; PG8_SCHED;
.LBB0_555:
	s_add_u32 s6, s4, 0x100
	s_addc_u32 s7, s5, 0
	s_cmp_eq_u32 s51, 28
	s_cselect_b32 s12, s35, s6
	s_cselect_b32 s13, s34, s7
	s_cselect_b32 s10, s39, s40
	s_cselect_b32 s11, s38, s49
	s_add_u32 s8, s12, 0x80
	s_addc_u32 s9, s13, 0
	s_add_i32 s56, 0, 0x10000
	s_add_i32 s57, 0, 0x14000
	ds_read_b128 v[26:29], v244
	ds_read_b128 v[30:33], v244 offset:1024
	ds_read_b128 v[98:101], v244 offset:2048
	ds_read_b128 v[102:105], v244 offset:3072
	ds_read_b128 v[146:149], v244 offset:16384
	ds_read_b128 v[150:153], v244 offset:17408
	ds_read_b128 v[154:157], v244 offset:18432
	ds_read_b128 v[158:161], v244 offset:19456
	s_add_u32 s4, s4, 0x80080
	s_addc_u32 s5, s5, 0
	ds_read_b128 v[178:181], v210
	ds_read_b128 v[182:185], v210 offset:1024
	ds_read_b128 v[186:189], v210 offset:2048
	ds_read_b128 v[190:193], v210 offset:3072
	ds_read_b128 v[194:197], v210 offset:4096
	ds_read_b128 v[198:201], v210 offset:5120
	ds_read_b128 v[202:205], v210 offset:6144
	ds_read_b128 v[212:215], v210 offset:7168
	s_add_i32 m0, s18, 0xc000
	s_nop 0
	global_load_lds_dwordx4 v1, s[4:5]
	s_add_i32 m0, s18, 0xe000
	s_nop 0
	global_load_lds_dwordx4 v164, s[4:5]
	s_waitcnt vmcnt(8)
	s_waitcnt lgkmcnt(0)
	s_barrier
	s_waitcnt lgkmcnt(0)
	v_mfma_f32_16x16x32_bf16 v[142:145], v[26:29], v[178:181], v[142:145]
	v_mfma_f32_16x16x32_bf16 v[142:145], v[30:33], v[182:185], v[142:145]
	v_mfma_f32_16x16x32_bf16 v[134:137], v[26:29], v[186:189], v[134:137]
	v_mfma_f32_16x16x32_bf16 v[134:137], v[30:33], v[190:193], v[134:137]
	v_mfma_f32_16x16x32_bf16 v[126:129], v[26:29], v[194:197], v[126:129]
	v_mfma_f32_16x16x32_bf16 v[126:129], v[30:33], v[198:201], v[126:129]
	v_mfma_f32_16x16x32_bf16 v[118:121], v[26:29], v[202:205], v[118:121]
	v_mfma_f32_16x16x32_bf16 v[118:121], v[30:33], v[212:215], v[118:121]
	v_mfma_f32_16x16x32_bf16 v[138:141], v[98:101], v[178:181], v[138:141]
	v_mfma_f32_16x16x32_bf16 v[138:141], v[102:105], v[182:185], v[138:141]
	v_mfma_f32_16x16x32_bf16 v[130:133], v[98:101], v[186:189], v[130:133]
	v_mfma_f32_16x16x32_bf16 v[130:133], v[102:105], v[190:193], v[130:133]
	v_mfma_f32_16x16x32_bf16 v[122:125], v[98:101], v[194:197], v[122:125]
	v_mfma_f32_16x16x32_bf16 v[122:125], v[102:105], v[198:201], v[122:125]
	v_mfma_f32_16x16x32_bf16 v[114:117], v[98:101], v[202:205], v[114:117]
	v_mfma_f32_16x16x32_bf16 v[114:117], v[102:105], v[212:215], v[114:117]
	v_mfma_f32_16x16x32_bf16 v[70:73], v[146:149], v[178:181], v[70:73]
	v_mfma_f32_16x16x32_bf16 v[70:73], v[150:153], v[182:185], v[70:73]
	v_mfma_f32_16x16x32_bf16 v[62:65], v[146:149], v[186:189], v[62:65]
	v_mfma_f32_16x16x32_bf16 v[62:65], v[150:153], v[190:193], v[62:65]
	v_mfma_f32_16x16x32_bf16 v[54:57], v[146:149], v[194:197], v[54:57]
	v_mfma_f32_16x16x32_bf16 v[54:57], v[150:153], v[198:201], v[54:57]
	v_mfma_f32_16x16x32_bf16 v[46:49], v[146:149], v[202:205], v[46:49]
	v_mfma_f32_16x16x32_bf16 v[46:49], v[150:153], v[212:215], v[46:49]
	v_mfma_f32_16x16x32_bf16 v[66:69], v[154:157], v[178:181], v[66:69]
	v_mfma_f32_16x16x32_bf16 v[66:69], v[158:161], v[182:185], v[66:69]
	v_mfma_f32_16x16x32_bf16 v[58:61], v[154:157], v[186:189], v[58:61]
	v_mfma_f32_16x16x32_bf16 v[58:61], v[158:161], v[190:193], v[58:61]
	v_mfma_f32_16x16x32_bf16 v[50:53], v[154:157], v[194:197], v[50:53]
	v_mfma_f32_16x16x32_bf16 v[50:53], v[158:161], v[198:201], v[50:53]
	v_mfma_f32_16x16x32_bf16 v[42:45], v[154:157], v[202:205], v[42:45]
	v_mfma_f32_16x16x32_bf16 v[42:45], v[158:161], v[212:215], v[42:45]
	s_barrier
	s_mov_b64 s[4:5], s[10:11]
	s_add_i32 s56, s56, s17
	ds_read_b128 v[178:181], v210 offset:16384
	ds_read_b128 v[182:185], v210 offset:17408
	ds_read_b128 v[186:189], v210 offset:18432
	ds_read_b128 v[190:193], v210 offset:19456
	ds_read_b128 v[194:197], v210 offset:20480
	ds_read_b128 v[198:201], v210 offset:21504
	ds_read_b128 v[202:205], v210 offset:22528
	ds_read_b128 v[212:215], v210 offset:23552
	s_mov_b32 m0, s56
	s_nop 0
	global_load_lds_dwordx4 v162, s[4:5]
	s_add_i32 m0, s56, 0x2000
	s_nop 0
	global_load_lds_dwordx4 v206, s[4:5]
	s_add_u32 s4, s10, 0x80000
	s_addc_u32 s5, s11, 0
	s_add_i32 s56, s57, s17
	s_mov_b32 m0, s56
	s_nop 0
	global_load_lds_dwordx4 v162, s[4:5]
	s_add_i32 m0, s56, 0x2000
	s_nop 0
	global_load_lds_dwordx4 v206, s[4:5]
	s_mov_b64 s[4:5], s[12:13]
	s_mov_b32 m0, s18
	s_nop 0
	global_load_lds_dwordx4 v1, s[4:5]
	s_mov_b32 m0, s19
	s_nop 0
	global_load_lds_dwordx4 v164, s[4:5]
	s_waitcnt vmcnt(8)
	s_waitcnt lgkmcnt(0)
	s_barrier
	s_waitcnt lgkmcnt(0)
	v_mfma_f32_16x16x32_bf16 v[110:113], v[26:29], v[178:181], v[110:113]
	v_mfma_f32_16x16x32_bf16 v[110:113], v[30:33], v[182:185], v[110:113]
	v_mfma_f32_16x16x32_bf16 v[94:97], v[26:29], v[186:189], v[94:97]
	v_mfma_f32_16x16x32_bf16 v[94:97], v[30:33], v[190:193], v[94:97]
	v_mfma_f32_16x16x32_bf16 v[86:89], v[26:29], v[194:197], v[86:89]
	v_mfma_f32_16x16x32_bf16 v[86:89], v[30:33], v[198:201], v[86:89]
	v_mfma_f32_16x16x32_bf16 v[26:29], v[26:29], v[202:205], v[78:81]
	v_mfma_f32_16x16x32_bf16 v[26:29], v[30:33], v[212:215], v[26:29]
	v_mfma_f32_16x16x32_bf16 v[106:109], v[98:101], v[178:181], v[106:109]
	v_mfma_f32_16x16x32_bf16 v[106:109], v[102:105], v[182:185], v[106:109]
	v_mfma_f32_16x16x32_bf16 v[90:93], v[98:101], v[186:189], v[90:93]
	v_mfma_f32_16x16x32_bf16 v[90:93], v[102:105], v[190:193], v[90:93]
	v_mfma_f32_16x16x32_bf16 v[82:85], v[98:101], v[194:197], v[82:85]
	v_mfma_f32_16x16x32_bf16 v[82:85], v[102:105], v[198:201], v[82:85]
	v_mfma_f32_16x16x32_bf16 v[30:33], v[98:101], v[202:205], v[74:77]
	v_mfma_f32_16x16x32_bf16 v[30:33], v[102:105], v[212:215], v[30:33]
	v_mfma_f32_16x16x32_bf16 v[38:41], v[146:149], v[178:181], v[38:41]
	v_mfma_f32_16x16x32_bf16 v[38:41], v[150:153], v[182:185], v[38:41]
	v_mfma_f32_16x16x32_bf16 v[22:25], v[146:149], v[186:189], v[22:25]
	v_mfma_f32_16x16x32_bf16 v[22:25], v[150:153], v[190:193], v[22:25]
	v_mfma_f32_16x16x32_bf16 v[14:17], v[146:149], v[194:197], v[14:17]
	v_mfma_f32_16x16x32_bf16 v[14:17], v[150:153], v[198:201], v[14:17]
	v_mfma_f32_16x16x32_bf16 v[6:9], v[146:149], v[202:205], v[6:9]
	v_mfma_f32_16x16x32_bf16 v[6:9], v[150:153], v[212:215], v[6:9]
	v_mfma_f32_16x16x32_bf16 v[34:37], v[154:157], v[178:181], v[34:37]
	v_mfma_f32_16x16x32_bf16 v[34:37], v[158:161], v[182:185], v[34:37]
	v_mfma_f32_16x16x32_bf16 v[18:21], v[154:157], v[186:189], v[18:21]
	v_mfma_f32_16x16x32_bf16 v[18:21], v[158:161], v[190:193], v[18:21]
	v_mfma_f32_16x16x32_bf16 v[10:13], v[154:157], v[194:197], v[10:13]
	v_mfma_f32_16x16x32_bf16 v[10:13], v[158:161], v[198:201], v[10:13]
	v_mfma_f32_16x16x32_bf16 v[2:5], v[154:157], v[202:205], v[2:5]
	v_mfma_f32_16x16x32_bf16 v[2:5], v[158:161], v[212:215], v[2:5]
	s_barrier
; #define PG8_STAGE(bufoff, gbase, voff) do { const char* gb_ = (const char*)(gbase); asm volatile("" : "+s"(gb_)); _Pragma("unroll") for (int _i = 0; _i < 2; ++_i) { unsigned vo_ = (voff)[_i]; asm volatile("" : "+v"(vo_));        \
;         __builtin_amdgcn_global_load_lds((const unsigned*)(gb_ + vo_), (PG8_LAS unsigned*)(lds + (bufoff) + ldsw + _i * 8192), 16, 0, 0); } } while (0)
; #define PG8_LDA(dst, b, h) do { _Pragma("unroll") for (int m = 0; m < 4; ++m) _Pragma("unroll") for (int k = 0; k < 2; ++k) dst[m][k] = *(const PG8_LAS bf16x8*)(lds + PG8_SA(b, h) + aoff + m * 2048 + k * 1024); } while (0)
; #define PG8_LDB(dst, b, h) do { _Pragma("unroll") for (int n = 0; n < 2; ++n) _Pragma("unroll") for (int k = 0; k < 2; ++k) dst[n][k] = *(const PG8_LAS bf16x8*)(lds + PG8_SB(b, h) + boff + n * 2048 + k * 1024); } while (0)
; #define PG8_MMA(ai, bj, At, Bt) do { __builtin_amdgcn_s_setprio(1); _Pragma("unroll") for (int m = 0; m < 4; ++m) _Pragma("unroll") for (int n = 0; n < 2; ++n) _Pragma("unroll") for (int k = 0; k < 2; ++k) \
;         acc[ai][bj][m][n] = __builtin_amdgcn_mfma_f32_16x16x32_bf16(Bt[n][k], At[m][k], acc[ai][bj][m][n], 0, 0, 0); __builtin_amdgcn_s_setprio(0); } while (0)
; #define PG8_WAIT_V(n) asm volatile("s_waitcnt vmcnt(" #n ")" ::: "memory")
; #define PG8_WAIT_L(n) asm volatile("s_waitcnt lgkmcnt(" #n ")" ::: "memory")
; #define PG8_BAR __builtin_amdgcn_s_barrier()
; #define PG8_SCHED __builtin_amdgcn_sched_barrier(0)
; template <class Epi, class Sched, bool ALIGN_EPI = false, bool SP2 = false>
; __device__ __forceinline__ void gemm_phase(PG8_LAS unsigned char* lds, const Gemm g, const Sched& S, const Epi& E) {
;     ...
;             PG8_LDB(B0, 1, 0); PG8_LDB(B1, 1, 1); PG8_SCHED; PG8_LDA(At, 1, 0); PG8_STAGE(PG8_SA(0, 1), a2 + hstep, voffA);
;             PG8_WAIT_V(8); PG8_WAIT_L(0); PG8_BAR; PG8_MMA(0, 0, At, B0); PG8_MMA(0, 1, At, B1); PG8_BAR; PG8_SCHED;
;             PG8_LDA(At, 1, 1); PG8_STAGE(PG8_SB(1, 0), b3, voffB); PG8_STAGE(PG8_SB(1, 1), b3 + hstep, voffB); PG8_STAGE(PG8_SA(1, 0), a3, voffA);
;             PG8_WAIT_V(8); PG8_WAIT_L(0); PG8_BAR; PG8_MMA(1, 0, At, B0); PG8_MMA(1, 1, At, B1); PG8_BAR; PG8_SCHED;
	s_add_i32 s56, 0, 0x18000
	s_add_i32 s57, 0, 0x1c000
	ds_read_b128 v[74:77], v244 offset:32768
	ds_read_b128 v[78:81], v244 offset:33792
	ds_read_b128 v[98:101], v244 offset:34816
	ds_read_b128 v[102:105], v244 offset:35840
	ds_read_b128 v[146:149], v244 offset:49152
	ds_read_b128 v[150:153], v244 offset:50176
	ds_read_b128 v[154:157], v244 offset:51200
	ds_read_b128 v[158:161], v244 offset:52224
	s_add_u32 s4, s12, 0x80000
	s_addc_u32 s5, s13, 0
	s_mov_b32 m0, s20
	ds_read_b128 v[178:181], v210 offset:32768
	ds_read_b128 v[182:185], v210 offset:33792
	ds_read_b128 v[186:189], v210 offset:34816
	ds_read_b128 v[190:193], v210 offset:35840
	ds_read_b128 v[194:197], v210 offset:36864
	ds_read_b128 v[198:201], v210 offset:37888
	ds_read_b128 v[202:205], v210 offset:38912
	ds_read_b128 v[212:215], v210 offset:39936
	s_nop 0
	global_load_lds_dwordx4 v1, s[4:5]
	s_mov_b32 m0, s21
	s_nop 0
	global_load_lds_dwordx4 v164, s[4:5]
	s_waitcnt vmcnt(8)
	s_waitcnt lgkmcnt(0)
	s_barrier
	s_waitcnt lgkmcnt(0)
	v_mfma_f32_16x16x32_bf16 v[142:145], v[74:77], v[178:181], v[142:145]
	v_mfma_f32_16x16x32_bf16 v[142:145], v[78:81], v[182:185], v[142:145]
	v_mfma_f32_16x16x32_bf16 v[134:137], v[74:77], v[186:189], v[134:137]
	v_mfma_f32_16x16x32_bf16 v[134:137], v[78:81], v[190:193], v[134:137]
	v_mfma_f32_16x16x32_bf16 v[126:129], v[74:77], v[194:197], v[126:129]
	v_mfma_f32_16x16x32_bf16 v[126:129], v[78:81], v[198:201], v[126:129]
	v_mfma_f32_16x16x32_bf16 v[118:121], v[74:77], v[202:205], v[118:121]
	v_mfma_f32_16x16x32_bf16 v[118:121], v[78:81], v[212:215], v[118:121]
	v_mfma_f32_16x16x32_bf16 v[138:141], v[98:101], v[178:181], v[138:141]
	v_mfma_f32_16x16x32_bf16 v[138:141], v[102:105], v[182:185], v[138:141]
	v_mfma_f32_16x16x32_bf16 v[130:133], v[98:101], v[186:189], v[130:133]
	v_mfma_f32_16x16x32_bf16 v[130:133], v[102:105], v[190:193], v[130:133]
	v_mfma_f32_16x16x32_bf16 v[122:125], v[98:101], v[194:197], v[122:125]
	v_mfma_f32_16x16x32_bf16 v[122:125], v[102:105], v[198:201], v[122:125]
	v_mfma_f32_16x16x32_bf16 v[114:117], v[98:101], v[202:205], v[114:117]
	v_mfma_f32_16x16x32_bf16 v[114:117], v[102:105], v[212:215], v[114:117]
	v_mfma_f32_16x16x32_bf16 v[70:73], v[146:149], v[178:181], v[70:73]
	v_mfma_f32_16x16x32_bf16 v[70:73], v[150:153], v[182:185], v[70:73]
	v_mfma_f32_16x16x32_bf16 v[62:65], v[146:149], v[186:189], v[62:65]
	v_mfma_f32_16x16x32_bf16 v[62:65], v[150:153], v[190:193], v[62:65]
	v_mfma_f32_16x16x32_bf16 v[54:57], v[146:149], v[194:197], v[54:57]
	v_mfma_f32_16x16x32_bf16 v[54:57], v[150:153], v[198:201], v[54:57]
	v_mfma_f32_16x16x32_bf16 v[46:49], v[146:149], v[202:205], v[46:49]
	v_mfma_f32_16x16x32_bf16 v[46:49], v[150:153], v[212:215], v[46:49]
	v_mfma_f32_16x16x32_bf16 v[66:69], v[154:157], v[178:181], v[66:69]
	v_mfma_f32_16x16x32_bf16 v[66:69], v[158:161], v[182:185], v[66:69]
	v_mfma_f32_16x16x32_bf16 v[58:61], v[154:157], v[186:189], v[58:61]
	v_mfma_f32_16x16x32_bf16 v[58:61], v[158:161], v[190:193], v[58:61]
	v_mfma_f32_16x16x32_bf16 v[50:53], v[154:157], v[194:197], v[50:53]
	v_mfma_f32_16x16x32_bf16 v[50:53], v[158:161], v[198:201], v[50:53]
	v_mfma_f32_16x16x32_bf16 v[42:45], v[154:157], v[202:205], v[42:45]
	v_mfma_f32_16x16x32_bf16 v[42:45], v[158:161], v[212:215], v[42:45]
	s_barrier
	s_add_u32 s4, s10, 0x80
	s_addc_u32 s5, s11, 0
	s_add_i32 s12, s56, s17
	ds_read_b128 v[178:181], v210 offset:49152
	ds_read_b128 v[182:185], v210 offset:50176
	ds_read_b128 v[186:189], v210 offset:51200
	ds_read_b128 v[190:193], v210 offset:52224
	ds_read_b128 v[194:197], v210 offset:53248
	ds_read_b128 v[198:201], v210 offset:54272
	ds_read_b128 v[202:205], v210 offset:55296
	ds_read_b128 v[212:215], v210 offset:56320
	s_mov_b32 m0, s12
	s_nop 0
	global_load_lds_dwordx4 v162, s[4:5]
	s_add_i32 m0, s12, 0x2000
	s_nop 0
	global_load_lds_dwordx4 v206, s[4:5]
	s_add_u32 s4, s10, 0x80080
	s_addc_u32 s5, s11, 0
	s_add_i32 s10, s57, s17
	s_mov_b32 m0, s10
	s_nop 0
	global_load_lds_dwordx4 v162, s[4:5]
	s_add_i32 m0, s10, 0x2000
	s_nop 0
	global_load_lds_dwordx4 v206, s[4:5]
	s_mov_b32 m0, s26
	s_nop 0
	global_load_lds_dwordx4 v1, s[8:9]
	s_mov_b32 m0, s27
	s_nop 0
	global_load_lds_dwordx4 v164, s[8:9]
	s_waitcnt vmcnt(8)
	s_waitcnt lgkmcnt(0)
	s_barrier
	s_waitcnt lgkmcnt(0)
	v_mfma_f32_16x16x32_bf16 v[110:113], v[74:77], v[178:181], v[110:113]
	v_mfma_f32_16x16x32_bf16 v[110:113], v[78:81], v[182:185], v[110:113]
	v_mfma_f32_16x16x32_bf16 v[94:97], v[74:77], v[186:189], v[94:97]
	v_mfma_f32_16x16x32_bf16 v[94:97], v[78:81], v[190:193], v[94:97]
	v_mfma_f32_16x16x32_bf16 v[86:89], v[74:77], v[194:197], v[86:89]
	v_mfma_f32_16x16x32_bf16 v[86:89], v[78:81], v[198:201], v[86:89]
	v_mfma_f32_16x16x32_bf16 v[26:29], v[74:77], v[202:205], v[26:29]
	v_mfma_f32_16x16x32_bf16 v[78:81], v[78:81], v[212:215], v[26:29]
	v_mfma_f32_16x16x32_bf16 v[106:109], v[98:101], v[178:181], v[106:109]
	v_mfma_f32_16x16x32_bf16 v[106:109], v[102:105], v[182:185], v[106:109]
	v_mfma_f32_16x16x32_bf16 v[90:93], v[98:101], v[186:189], v[90:93]
	v_mfma_f32_16x16x32_bf16 v[90:93], v[102:105], v[190:193], v[90:93]
	v_mfma_f32_16x16x32_bf16 v[82:85], v[98:101], v[194:197], v[82:85]
	v_mfma_f32_16x16x32_bf16 v[82:85], v[102:105], v[198:201], v[82:85]
	v_mfma_f32_16x16x32_bf16 v[26:29], v[98:101], v[202:205], v[30:33]
	v_mfma_f32_16x16x32_bf16 v[74:77], v[102:105], v[212:215], v[26:29]
	v_mfma_f32_16x16x32_bf16 v[26:29], v[146:149], v[178:181], v[38:41]
	v_mfma_f32_16x16x32_bf16 v[38:41], v[150:153], v[182:185], v[26:29]
	v_mfma_f32_16x16x32_bf16 v[22:25], v[146:149], v[186:189], v[22:25]
	v_mfma_f32_16x16x32_bf16 v[22:25], v[150:153], v[190:193], v[22:25]
	v_mfma_f32_16x16x32_bf16 v[14:17], v[146:149], v[194:197], v[14:17]
	v_mfma_f32_16x16x32_bf16 v[14:17], v[150:153], v[198:201], v[14:17]
	v_mfma_f32_16x16x32_bf16 v[6:9], v[146:149], v[202:205], v[6:9]
	v_mfma_f32_16x16x32_bf16 v[6:9], v[150:153], v[212:215], v[6:9]
	v_mfma_f32_16x16x32_bf16 v[26:29], v[154:157], v[178:181], v[34:37]
	v_mfma_f32_16x16x32_bf16 v[34:37], v[158:161], v[182:185], v[26:29]
	v_mfma_f32_16x16x32_bf16 v[18:21], v[154:157], v[186:189], v[18:21]
	v_mfma_f32_16x16x32_bf16 v[18:21], v[158:161], v[190:193], v[18:21]
	v_mfma_f32_16x16x32_bf16 v[10:13], v[154:157], v[194:197], v[10:13]
	v_mfma_f32_16x16x32_bf16 v[10:13], v[158:161], v[198:201], v[10:13]
	v_mfma_f32_16x16x32_bf16 v[2:5], v[154:157], v[202:205], v[2:5]
	v_mfma_f32_16x16x32_bf16 v[2:5], v[158:161], v[212:215], v[2:5]
	s_barrier
;     __device__ __forceinline__ void operator()(const f32x4 (&acc)[2][2][4][2], const Unit& u, int wr, int wc, int fr, int fq) const {
;         const int row0 = u.pm * BM + wr * 64 + fr, col0 = u.pn * BM + wc * 32 + 8 * fq, b = (u.pm * BM) / rows_per_batch;
;         const float* g = gate + (size_t)b * gate_bstride + col0;
;         float ssq[2][4];
; #pragma unroll
;         for (int ai = 0; ai < 2; ++ai)
; #pragma unroll
;             for (int m = 0; m < 4; ++m) ssq[ai][m] = 0.f;
;         f32x4 gv[2][2], Gv[2][2];
; #pragma unroll
;         for (int bj = 0; bj < 2; ++bj) { gv[bj][0] = *(const f32x4*)(g + bj * HALF); gv[bj][1] = *(const f32x4*)(g + bj * HALF + 4); Gv[bj][0] = (f32x4){0.f, 0.f, 0.f, 0.f}; Gv[bj][1] = (f32x4){0.f, 0.f, 0.f, 0.f};
;             if (Hn) { const float* sc = scnext + (size_t)b * gate_bstride + col0 + bj * HALF;
;                 Gv[bj][0] = *(const f32x4*)(gnext + col0 + bj * HALF) * (1.0f + *(const f32x4*)(sc)); Gv[bj][1] = *(const f32x4*)(gnext + col0 + bj * HALF + 4) * (1.0f + *(const f32x4*)(sc + 4)); } }
; #pragma unroll
;         for (int bj = 0; bj < 2; ++bj) {
;             const f32x4 g0 = gv[bj][0], g1 = gv[bj][1], G0 = Gv[bj][0], G1 = Gv[bj][1];
; #pragma unroll
;             for (int ai = 0; ai < 2; ++ai)
; #pragma unroll
;                 for (int m = 0; m < 4; ++m) { const size_t off = (size_t)(row0 + ai * HALF + m * 16) * 2048 + col0 + bj * HALF;
;                     f32x4 x0 = __builtin_nontemporal_load((const f32x4*)(base + off)), x1 = __builtin_nontemporal_load((const f32x4*)(base + off + 4));
;                     if constexpr (HAS_DIN) { const u32x4 dw = __builtin_nontemporal_load((const u32x4*)(dbuf + off));
;                         x0 += (f32x4){__builtin_bit_cast(float, dw.x << 16), __builtin_bit_cast(float, dw.x & 0xffff0000u), __builtin_bit_cast(float, dw.y << 16), __builtin_bit_cast(float, dw.y & 0xffff0000u)};
;                         x1 += (f32x4){__builtin_bit_cast(float, dw.z << 16), __builtin_bit_cast(float, dw.z & 0xffff0000u), __builtin_bit_cast(float, dw.w << 16), __builtin_bit_cast(float, dw.w & 0xffff0000u)}; }
;                     f32x4 o0, o1;
;                     if constexpr (OUT_DELTA) { const f32x4 d0 = g0 * acc[ai][bj][m][0], d1 = g1 * acc[ai][bj][m][1];
	s_add_i32 s51, s51, 2
	s_add_u32 s40, s40, 0x100
	s_addc_u32 s49, s49, 0
	s_cmp_gt_u32 s51, 29
	s_mov_b64 s[4:5], s[6:7]
	s_cbranch_scc0 .LBB0_555
	s_ashr_i32 s4, s29, 31
	s_lshr_b32 s4, s4, 27
	s_add_i32 s4, s29, s4
	s_ashr_i32 s4, s4, 5
	v_lshl_or_b32 v148, s33, 8, v209
	s_mul_i32 s7, s4, 0xc000
	v_ashrrev_i32_e32 v149, 31, v148
	s_mul_hi_i32 s6, s4, 0xc000
	s_add_u32 s4, s22, s7
	s_addc_u32 s5, s23, s6
	v_lshlrev_b64 v[26:27], 2, v[148:149]
	v_lshl_add_u64 v[146:147], s[4:5], 0, v[26:27]
	s_add_u32 s4, s24, s7
	s_addc_u32 s5, s25, s6
	v_lshl_add_u64 v[160:161], s[4:5], 0, v[26:27]
	v_lshl_add_u64 v[178:179], s[46:47], 0, v[26:27]
	global_load_dwordx4 v[98:101], v[146:147], off offset:16
	global_load_dwordx4 v[102:105], v[146:147], off
	global_load_dwordx4 v[26:29], v[178:179], off offset:16
	global_load_dwordx4 v[30:33], v[178:179], off
	global_load_dwordx4 v[150:153], v[160:161], off offset:16
	global_load_dwordx4 v[154:157], v[160:161], off
	s_mov_b64 s[4:5], 0x40000
	s_waitcnt vmcnt(0)
	v_pk_mul_f32 v[188:189], v[140:141], v[100:101]
	v_pk_mul_f32 v[142:143], v[142:143], v[102:103]
	v_pk_mul_f32 v[144:145], v[144:145], v[104:105]
	v_pk_mul_f32 v[140:141], v[138:139], v[98:99]
	v_pk_mul_f32 v[136:137], v[136:137], v[104:105]
	v_pk_add_f32 v[156:157], v[156:157], 1.0 op_sel_hi:[1,0]
	v_pk_add_f32 v[154:155], v[154:155], 1.0 op_sel_hi:[1,0]
	v_pk_mul_f32 v[198:199], v[32:33], v[156:157]
	v_pk_mul_f32 v[200:201], v[30:31], v[154:155]
	v_pk_add_f32 v[30:31], v[152:153], 1.0 op_sel_hi:[1,0]
	v_pk_add_f32 v[32:33], v[150:151], 1.0 op_sel_hi:[1,0]
	v_pk_mul_f32 v[202:203], v[28:29], v[30:31]
	v_pk_mul_f32 v[204:205], v[26:27], v[32:33]
	global_load_dwordx4 v[26:29], v[146:147], off offset:528
	global_load_dwordx4 v[30:33], v[146:147], off offset:512
	global_load_dwordx4 v[156:159], v[178:179], off offset:528
	global_load_dwordx4 v[152:155], v[178:179], off offset:512
	s_nop 0
	global_load_dwordx4 v[178:181], v[160:161], off offset:528
	global_load_dwordx4 v[182:185], v[160:161], off offset:512
	v_pk_mul_f32 v[134:135], v[134:135], v[102:103]
	v_pk_mul_f32 v[130:131], v[130:131], v[98:99]
	v_pk_mul_f32 v[132:133], v[132:133], v[100:101]
	v_pk_mul_f32 v[128:129], v[128:129], v[104:105]
	v_pk_mul_f32 v[126:127], v[126:127], v[102:103]
	v_pk_mul_f32 v[122:123], v[122:123], v[98:99]
	v_pk_mul_f32 v[124:125], v[124:125], v[100:101]
	v_pk_mul_f32 v[120:121], v[120:121], v[104:105]
	v_pk_mul_f32 v[118:119], v[118:119], v[102:103]
	v_pk_mul_f32 v[114:115], v[114:115], v[98:99]
	v_pk_mul_f32 v[116:117], v[116:117], v[100:101]
	v_pk_mul_f32 v[112:113], v[112:113], v[104:105]
	v_pk_mul_f32 v[110:111], v[110:111], v[102:103]
	v_pk_mul_f32 v[106:107], v[106:107], v[98:99]
	v_pk_mul_f32 v[108:109], v[108:109], v[100:101]
	v_pk_mul_f32 v[96:97], v[96:97], v[104:105]
	v_pk_mul_f32 v[94:95], v[94:95], v[102:103]
	v_pk_mul_f32 v[90:91], v[90:91], v[98:99]
	v_pk_mul_f32 v[92:93], v[92:93], v[100:101]
	v_pk_mul_f32 v[88:89], v[88:89], v[104:105]
	v_pk_mul_f32 v[86:87], v[86:87], v[102:103]
	v_pk_mul_f32 v[82:83], v[82:83], v[98:99]
	v_pk_mul_f32 v[84:85], v[84:85], v[100:101]
	v_pk_mul_f32 v[80:81], v[80:81], v[104:105]
	v_pk_mul_f32 v[78:79], v[78:79], v[102:103]
	v_pk_mul_f32 v[74:75], v[74:75], v[98:99]
	v_pk_mul_f32 v[76:77], v[76:77], v[100:101]
	s_waitcnt vmcnt(5)
	v_pk_mul_f32 v[58:59], v[58:59], v[26:27]
	s_waitcnt vmcnt(4)
	v_pk_mul_f32 v[72:73], v[72:73], v[32:33]
	v_pk_mul_f32 v[70:71], v[70:71], v[30:31]
	v_pk_mul_f32 v[64:65], v[64:65], v[32:33]
	v_pk_mul_f32 v[62:63], v[62:63], v[30:31]
	s_waitcnt vmcnt(0)
	v_pk_add_f32 v[146:147], v[184:185], 1.0 op_sel_hi:[1,0]
	v_pk_add_f32 v[160:161], v[182:183], 1.0 op_sel_hi:[1,0]
	v_pk_mul_f32 v[150:151], v[154:155], v[146:147]
	v_pk_add_f32 v[146:147], v[180:181], 1.0 op_sel_hi:[1,0]
	v_pk_mul_f32 v[152:153], v[152:153], v[160:161]
	v_pk_mul_f32 v[154:155], v[158:159], v[146:147]
	v_lshl_add_u32 v146, s29, 8, v207
	v_ashrrev_i32_e32 v147, 31, v146
	v_lshlrev_b64 v[184:185], 11, v[146:147]
	v_lshl_add_u64 v[186:187], v[184:185], 0, v[148:149]
	v_pk_add_f32 v[160:161], v[178:179], 1.0 op_sel_hi:[1,0]
	v_lshl_add_u64 v[178:179], v[186:187], 2, s[44:45]
	v_pk_mul_f32 v[156:157], v[156:157], v[160:161]
	global_load_dwordx4 v[158:161], v[178:179], off nt
	global_load_dwordx4 v[180:183], v[178:179], off offset:16 nt
	v_cvt_pk_bf16_f32 v138, v142, v143
	v_lshlrev_b64 v[142:143], 1, v[186:187]
	v_cvt_pk_bf16_f32 v139, v144, v145
	v_cvt_pk_bf16_f32 v140, v140, v141
	v_cvt_pk_bf16_f32 v141, v188, v189
	v_lshl_add_u64 v[144:145], s[90:91], 0, v[142:143]
	global_store_dwordx4 v[144:145], v[138:141], off
	v_lshlrev_b32_e32 v144, 16, v140
	v_and_b32_e32 v145, 0xffff0000, v140
	v_lshlrev_b32_e32 v140, 16, v141
	v_and_b32_e32 v141, 0xffff0000, v141
	v_lshl_add_u64 v[142:143], s[96:97], 0, v[142:143]
	v_pk_mul_f32 v[60:61], v[60:61], v[28:29]
	v_pk_mul_f32 v[56:57], v[56:57], v[32:33]
	v_pk_mul_f32 v[54:55], v[54:55], v[30:31]
	v_pk_mul_f32 v[50:51], v[50:51], v[26:27]
	v_pk_mul_f32 v[52:53], v[52:53], v[28:29]
	v_pk_mul_f32 v[48:49], v[48:49], v[32:33]
	v_pk_mul_f32 v[46:47], v[46:47], v[30:31]
	v_pk_mul_f32 v[42:43], v[42:43], v[26:27]
	v_pk_mul_f32 v[44:45], v[44:45], v[28:29]
	v_pk_mul_f32 v[40:41], v[40:41], v[32:33]
	v_pk_mul_f32 v[38:39], v[38:39], v[30:31]
	v_pk_mul_f32 v[34:35], v[34:35], v[26:27]
	v_pk_mul_f32 v[36:37], v[36:37], v[28:29]
	v_pk_mul_f32 v[24:25], v[24:25], v[32:33]
	v_pk_mul_f32 v[22:23], v[22:23], v[30:31]
	v_pk_mul_f32 v[18:19], v[18:19], v[26:27]
	v_pk_mul_f32 v[20:21], v[20:21], v[28:29]
	v_pk_mul_f32 v[16:17], v[16:17], v[32:33]
	v_pk_mul_f32 v[14:15], v[14:15], v[30:31]
	v_pk_mul_f32 v[10:11], v[10:11], v[26:27]
	v_pk_mul_f32 v[12:13], v[12:13], v[28:29]
	v_pk_mul_f32 v[8:9], v[8:9], v[32:33]
	v_pk_mul_f32 v[6:7], v[6:7], v[30:31]
	v_pk_mul_f32 v[2:3], v[2:3], v[26:27]
	v_pk_mul_f32 v[4:5], v[4:5], v[28:29]
	s_waitcnt vmcnt(1)
; __device__ __forceinline__ unsigned cvt_pk_bf16(float lo, float hi) { unsigned r; asm volatile("v_cvt_pk_bf16_f32 %0, %1, %2" : "=v"(r) : "v"(lo), "v"(hi)); return r; }
;     __device__ __forceinline__ void operator()(const f32x4 (&acc)[2][2][4][2], const Unit& u, int wr, int wc, int fr, int fq) const {
;     ...
;                 for (int m = 0; m < 4; ++m) { const size_t off = (size_t)(row0 + ai * HALF + m * 16) * 2048 + col0 + bj * HALF;
;                     f32x4 x0 = __builtin_nontemporal_load((const f32x4*)(base + off)), x1 = __builtin_nontemporal_load((const f32x4*)(base + off + 4));
;                     if constexpr (HAS_DIN) { const u32x4 dw = __builtin_nontemporal_load((const u32x4*)(dbuf + off));
;                         x0 += (f32x4){__builtin_bit_cast(float, dw.x << 16), __builtin_bit_cast(float, dw.x & 0xffff0000u), __builtin_bit_cast(float, dw.y << 16), __builtin_bit_cast(float, dw.y & 0xffff0000u)};
;                         x1 += (f32x4){__builtin_bit_cast(float, dw.z << 16), __builtin_bit_cast(float, dw.z & 0xffff0000u), __builtin_bit_cast(float, dw.w << 16), __builtin_bit_cast(float, dw.w & 0xffff0000u)}; }
;                     f32x4 o0, o1;
;                     if constexpr (OUT_DELTA) { const f32x4 d0 = g0 * acc[ai][bj][m][0], d1 = g1 * acc[ai][bj][m][1];
;                         u32x4 w; w.x = cvt_pk_bf16(d0[0], d0[1]); w.y = cvt_pk_bf16(d0[2], d0[3]); w.z = cvt_pk_bf16(d1[0], d1[1]); w.w = cvt_pk_bf16(d1[2], d1[3]);
;                         *(u32x4*)(dbuf + off) = w;
;                         o0 = x0 + (f32x4){__builtin_bit_cast(float, w.x << 16), __builtin_bit_cast(float, w.x & 0xffff0000u), __builtin_bit_cast(float, w.y << 16), __builtin_bit_cast(float, w.y & 0xffff0000u)};
;                         o1 = x1 + (f32x4){__builtin_bit_cast(float, w.z << 16), __builtin_bit_cast(float, w.z & 0xffff0000u), __builtin_bit_cast(float, w.w << 16), __builtin_bit_cast(float, w.w & 0xffff0000u)}; }
;                     else { o0 = x0 + g0 * acc[ai][bj][m][0]; o1 = x1 + g1 * acc[ai][bj][m][1]; *(f32x4*)(out + off) = o0; *(f32x4*)(out + off + 4) = o1; }
;                     if (Hn) { const f32x4 h0 = o0 * G0, h1 = o1 * G1;
;                         u32x4 w; w.x = cvt_pk_bf16(h0[0], h0[1]); w.y = cvt_pk_bf16(h0[2], h0[3]); w.z = cvt_pk_bf16(h1[0], h1[1]); w.w = cvt_pk_bf16(h1[2], h1[3]);
;                         *(u32x4*)(Hn + off) = w;
	v_pk_add_f32 v[182:183], v[182:183], v[140:141]
	v_lshlrev_b32_e32 v140, 16, v138
	v_and_b32_e32 v141, 0xffff0000, v138
	v_lshlrev_b32_e32 v138, 16, v139
	v_and_b32_e32 v139, 0xffff0000, v139
	v_pk_add_f32 v[158:159], v[158:159], v[140:141]
	v_pk_add_f32 v[160:161], v[160:161], v[138:139]
	v_pk_mul_f32 v[138:139], v[200:201], v[158:159]
	v_pk_add_f32 v[144:145], v[180:181], v[144:145]
	v_pk_mul_f32 v[140:141], v[198:199], v[160:161]
	v_cvt_pk_bf16_f32 v138, v138, v139
	v_pk_mul_f32 v[180:181], v[202:203], v[182:183]
	v_cvt_pk_bf16_f32 v139, v140, v141
	v_pk_mul_f32 v[186:187], v[204:205], v[144:145]
	s_nop 0
	v_cvt_pk_bf16_f32 v140, v186, v187
	v_cvt_pk_bf16_f32 v141, v180, v181
	global_store_dwordx4 v[142:143], v[138:141], off
	s_nop 1
	v_mul_f32_e32 v138, v159, v159
	v_mul_f32_e32 v139, v161, v161
	v_fmac_f32_e32 v138, v158, v158
	v_fmac_f32_e32 v139, v160, v160
	v_add_f32_e32 v138, v138, v139
	v_mul_f32_e32 v139, v145, v145
	v_mul_f32_e32 v140, v183, v183
	v_fmac_f32_e32 v139, v144, v144
	v_fmac_f32_e32 v140, v182, v182
	v_add_f32_e32 v139, v139, v140
	v_add_f32_e32 v211, v138, v139
	v_or_b32_e32 v138, 16, v146
	v_ashrrev_i32_e32 v139, 31, v138
	v_lshlrev_b64 v[140:141], 11, v[138:139]
	v_lshl_add_u64 v[180:181], v[140:141], 0, v[148:149]
	v_lshl_add_u64 v[138:139], v[180:181], 2, s[44:45]
	global_load_dwordx4 v[142:145], v[138:139], off nt
	global_load_dwordx4 v[158:161], v[138:139], off offset:16 nt
	v_lshlrev_b64 v[180:181], 1, v[180:181]
	v_cvt_pk_bf16_f32 v134, v134, v135
	v_cvt_pk_bf16_f32 v135, v136, v137
	v_cvt_pk_bf16_f32 v136, v130, v131
	v_cvt_pk_bf16_f32 v137, v132, v133
	v_lshl_add_u64 v[130:131], s[90:91], 0, v[180:181]
	global_store_dwordx4 v[130:131], v[134:137], off
	v_lshlrev_b32_e32 v132, 16, v136
	v_and_b32_e32 v133, 0xffff0000, v136
	v_lshlrev_b32_e32 v130, 16, v137
	v_and_b32_e32 v131, 0xffff0000, v137
	v_lshlrev_b32_e32 v136, 16, v134
	v_and_b32_e32 v137, 0xffff0000, v134
	v_lshlrev_b32_e32 v134, 16, v135
	v_and_b32_e32 v135, 0xffff0000, v135
	s_waitcnt vmcnt(2)
	v_pk_add_f32 v[134:135], v[144:145], v[134:135]
	s_waitcnt vmcnt(1)
	v_pk_add_f32 v[130:131], v[160:161], v[130:131]
	v_pk_add_f32 v[136:137], v[142:143], v[136:137]
	v_pk_add_f32 v[132:133], v[158:159], v[132:133]
	v_pk_mul_f32 v[144:145], v[198:199], v[134:135]
	v_pk_mul_f32 v[142:143], v[200:201], v[136:137]
	v_pk_mul_f32 v[158:159], v[202:203], v[130:131]
	v_pk_mul_f32 v[160:161], v[204:205], v[132:133]
	v_cvt_pk_bf16_f32 v142, v142, v143
	v_cvt_pk_bf16_f32 v143, v144, v145
	s_nop 0
	v_cvt_pk_bf16_f32 v144, v160, v161
	v_cvt_pk_bf16_f32 v145, v158, v159
	v_lshl_add_u64 v[158:159], s[96:97], 0, v[180:181]
	global_store_dwordx4 v[158:159], v[142:145], off
	s_nop 1
	v_or_b32_e32 v142, 32, v146
	v_ashrrev_i32_e32 v143, 31, v142
	v_lshlrev_b64 v[144:145], 11, v[142:143]
	v_lshl_add_u64 v[186:187], v[144:145], 0, v[148:149]
	v_lshl_add_u64 v[142:143], v[186:187], 2, s[44:45]
	global_load_dwordx4 v[158:161], v[142:143], off nt
	global_load_dwordx4 v[180:183], v[142:143], off offset:16 nt
	v_lshlrev_b64 v[186:187], 1, v[186:187]
	v_cvt_pk_bf16_f32 v126, v126, v127
	v_cvt_pk_bf16_f32 v127, v128, v129
	v_cvt_pk_bf16_f32 v128, v122, v123
	v_cvt_pk_bf16_f32 v129, v124, v125
	v_lshl_add_u64 v[122:123], s[90:91], 0, v[186:187]
	global_store_dwordx4 v[122:123], v[126:129], off
	v_lshlrev_b32_e32 v124, 16, v128
	v_and_b32_e32 v125, 0xffff0000, v128
	v_lshlrev_b32_e32 v122, 16, v129
	v_and_b32_e32 v123, 0xffff0000, v129
	v_lshlrev_b32_e32 v128, 16, v126
	v_and_b32_e32 v129, 0xffff0000, v126
	v_lshlrev_b32_e32 v126, 16, v127
	v_and_b32_e32 v127, 0xffff0000, v127
	s_waitcnt vmcnt(2)
	v_pk_add_f32 v[126:127], v[160:161], v[126:127]
	s_waitcnt vmcnt(1)
	v_pk_add_f32 v[122:123], v[182:183], v[122:123]
	v_pk_add_f32 v[128:129], v[158:159], v[128:129]
	v_pk_add_f32 v[124:125], v[180:181], v[124:125]
	v_pk_mul_f32 v[160:161], v[198:199], v[126:127]
	v_pk_mul_f32 v[158:159], v[200:201], v[128:129]
	v_pk_mul_f32 v[180:181], v[202:203], v[122:123]
	v_pk_mul_f32 v[182:183], v[204:205], v[124:125]
	v_cvt_pk_bf16_f32 v158, v158, v159
	v_cvt_pk_bf16_f32 v159, v160, v161
	s_nop 0
	v_cvt_pk_bf16_f32 v160, v182, v183
	v_cvt_pk_bf16_f32 v161, v180, v181
	v_lshl_add_u64 v[180:181], s[96:97], 0, v[186:187]
	global_store_dwordx4 v[180:181], v[158:161], off
	s_nop 1
	v_or_b32_e32 v158, 48, v146
	v_ashrrev_i32_e32 v159, 31, v158
	v_lshlrev_b64 v[160:161], 11, v[158:159]
	v_lshl_add_u64 v[190:191], v[160:161], 0, v[148:149]
	v_lshl_add_u64 v[158:159], v[190:191], 2, s[44:45]
	global_load_dwordx4 v[180:183], v[158:159], off nt
	global_load_dwordx4 v[186:189], v[158:159], off offset:16 nt
	v_lshlrev_b64 v[190:191], 1, v[190:191]
	v_cvt_pk_bf16_f32 v118, v118, v119
	v_cvt_pk_bf16_f32 v119, v120, v121
	v_cvt_pk_bf16_f32 v120, v114, v115
	v_cvt_pk_bf16_f32 v121, v116, v117
	v_lshl_add_u64 v[114:115], s[90:91], 0, v[190:191]
	global_store_dwordx4 v[114:115], v[118:121], off
	v_lshlrev_b32_e32 v116, 16, v120
	v_and_b32_e32 v117, 0xffff0000, v120
	v_lshlrev_b32_e32 v114, 16, v121
	v_and_b32_e32 v115, 0xffff0000, v121
	v_lshlrev_b32_e32 v120, 16, v118
	v_and_b32_e32 v121, 0xffff0000, v118
	v_lshlrev_b32_e32 v118, 16, v119
	v_and_b32_e32 v119, 0xffff0000, v119
	s_waitcnt vmcnt(2)
	v_pk_add_f32 v[118:119], v[182:183], v[118:119]
	s_waitcnt vmcnt(1)
; __device__ __forceinline__ unsigned cvt_pk_bf16(float lo, float hi) { unsigned r; asm volatile("v_cvt_pk_bf16_f32 %0, %1, %2" : "=v"(r) : "v"(lo), "v"(hi)); return r; }
;     __device__ __forceinline__ void operator()(const f32x4 (&acc)[2][2][4][2], const Unit& u, int wr, int wc, int fr, int fq) const {
;     ...
;                 for (int m = 0; m < 4; ++m) { const size_t off = (size_t)(row0 + ai * HALF + m * 16) * 2048 + col0 + bj * HALF;
;                     f32x4 x0 = __builtin_nontemporal_load((const f32x4*)(base + off)), x1 = __builtin_nontemporal_load((const f32x4*)(base + off + 4));
;                     if constexpr (HAS_DIN) { const u32x4 dw = __builtin_nontemporal_load((const u32x4*)(dbuf + off));
;                         x0 += (f32x4){__builtin_bit_cast(float, dw.x << 16), __builtin_bit_cast(float, dw.x & 0xffff0000u), __builtin_bit_cast(float, dw.y << 16), __builtin_bit_cast(float, dw.y & 0xffff0000u)};
;                         x1 += (f32x4){__builtin_bit_cast(float, dw.z << 16), __builtin_bit_cast(float, dw.z & 0xffff0000u), __builtin_bit_cast(float, dw.w << 16), __builtin_bit_cast(float, dw.w & 0xffff0000u)}; }
;                     f32x4 o0, o1;
;                     if constexpr (OUT_DELTA) { const f32x4 d0 = g0 * acc[ai][bj][m][0], d1 = g1 * acc[ai][bj][m][1];
;                         u32x4 w; w.x = cvt_pk_bf16(d0[0], d0[1]); w.y = cvt_pk_bf16(d0[2], d0[3]); w.z = cvt_pk_bf16(d1[0], d1[1]); w.w = cvt_pk_bf16(d1[2], d1[3]);
;                         *(u32x4*)(dbuf + off) = w;
;                         o0 = x0 + (f32x4){__builtin_bit_cast(float, w.x << 16), __builtin_bit_cast(float, w.x & 0xffff0000u), __builtin_bit_cast(float, w.y << 16), __builtin_bit_cast(float, w.y & 0xffff0000u)};
;                         o1 = x1 + (f32x4){__builtin_bit_cast(float, w.z << 16), __builtin_bit_cast(float, w.z & 0xffff0000u), __builtin_bit_cast(float, w.w << 16), __builtin_bit_cast(float, w.w & 0xffff0000u)}; }
;                     else { o0 = x0 + g0 * acc[ai][bj][m][0]; o1 = x1 + g1 * acc[ai][bj][m][1]; *(f32x4*)(out + off) = o0; *(f32x4*)(out + off + 4) = o1; }
;                     if (Hn) { const f32x4 h0 = o0 * G0, h1 = o1 * G1;
;                         u32x4 w; w.x = cvt_pk_bf16(h0[0], h0[1]); w.y = cvt_pk_bf16(h0[2], h0[3]); w.z = cvt_pk_bf16(h1[0], h1[1]); w.w = cvt_pk_bf16(h1[2], h1[3]);
;                         *(u32x4*)(Hn + off) = w;
	v_pk_add_f32 v[114:115], v[188:189], v[114:115]
	v_pk_add_f32 v[120:121], v[180:181], v[120:121]
	v_pk_add_f32 v[116:117], v[186:187], v[116:117]
	v_pk_mul_f32 v[182:183], v[198:199], v[118:119]
	v_pk_mul_f32 v[180:181], v[200:201], v[120:121]
	v_pk_mul_f32 v[186:187], v[202:203], v[114:115]
	v_pk_mul_f32 v[188:189], v[204:205], v[116:117]
	v_cvt_pk_bf16_f32 v180, v180, v181
	v_cvt_pk_bf16_f32 v181, v182, v183
	s_nop 0
	v_cvt_pk_bf16_f32 v182, v188, v189
	v_cvt_pk_bf16_f32 v183, v186, v187
	v_lshl_add_u64 v[186:187], s[96:97], 0, v[190:191]
	global_store_dwordx4 v[186:187], v[180:183], off
	s_nop 1
	v_lshl_add_u64 v[182:183], v[184:185], 0, s[4:5]
	v_lshl_add_u64 v[194:195], v[182:183], 0, v[148:149]
	v_lshl_add_u64 v[180:181], v[194:195], 2, s[44:45]
	global_load_dwordx4 v[186:189], v[180:181], off nt
	global_load_dwordx4 v[190:193], v[180:181], off offset:16 nt
	v_lshlrev_b64 v[194:195], 1, v[194:195]
	v_cvt_pk_bf16_f32 v110, v110, v111
	v_cvt_pk_bf16_f32 v111, v112, v113
	v_cvt_pk_bf16_f32 v112, v106, v107
	v_cvt_pk_bf16_f32 v113, v108, v109
	v_lshl_add_u64 v[106:107], s[90:91], 0, v[194:195]
	global_store_dwordx4 v[106:107], v[110:113], off
	v_lshlrev_b32_e32 v108, 16, v112
	v_and_b32_e32 v109, 0xffff0000, v112
	v_lshlrev_b32_e32 v106, 16, v113
	v_and_b32_e32 v107, 0xffff0000, v113
	v_lshlrev_b32_e32 v112, 16, v110
	v_and_b32_e32 v113, 0xffff0000, v110
	v_lshlrev_b32_e32 v110, 16, v111
	v_and_b32_e32 v111, 0xffff0000, v111
	s_mov_b64 s[4:5], 0x48000
	s_waitcnt vmcnt(2)
	v_pk_add_f32 v[110:111], v[188:189], v[110:111]
	s_waitcnt vmcnt(1)
	v_pk_add_f32 v[106:107], v[192:193], v[106:107]
	v_pk_add_f32 v[112:113], v[186:187], v[112:113]
	v_pk_add_f32 v[108:109], v[190:191], v[108:109]
	v_pk_mul_f32 v[188:189], v[198:199], v[110:111]
	v_pk_mul_f32 v[186:187], v[200:201], v[112:113]
	v_pk_mul_f32 v[190:191], v[202:203], v[106:107]
	v_pk_mul_f32 v[192:193], v[204:205], v[108:109]
	v_cvt_pk_bf16_f32 v186, v186, v187
	v_cvt_pk_bf16_f32 v187, v188, v189
	s_nop 0
	v_cvt_pk_bf16_f32 v188, v192, v193
	v_cvt_pk_bf16_f32 v189, v190, v191
	v_lshl_add_u64 v[190:191], s[96:97], 0, v[194:195]
	global_store_dwordx4 v[190:191], v[186:189], off
	s_nop 1
	v_lshl_add_u64 v[188:189], v[184:185], 0, s[4:5]
	v_lshl_add_u64 v[212:213], v[188:189], 0, v[148:149]
	v_lshl_add_u64 v[186:187], v[212:213], 2, s[44:45]
	global_load_dwordx4 v[190:193], v[186:187], off nt
	global_load_dwordx4 v[194:197], v[186:187], off offset:16 nt
	v_lshlrev_b64 v[212:213], 1, v[212:213]
	v_cvt_pk_bf16_f32 v94, v94, v95
	v_cvt_pk_bf16_f32 v95, v96, v97
	v_cvt_pk_bf16_f32 v96, v90, v91
	v_cvt_pk_bf16_f32 v97, v92, v93
	v_lshl_add_u64 v[90:91], s[90:91], 0, v[212:213]
	global_store_dwordx4 v[90:91], v[94:97], off
	v_lshlrev_b32_e32 v92, 16, v96
	v_and_b32_e32 v93, 0xffff0000, v96
	v_lshlrev_b32_e32 v90, 16, v97
	v_and_b32_e32 v91, 0xffff0000, v97
	v_lshlrev_b32_e32 v96, 16, v94
	v_and_b32_e32 v97, 0xffff0000, v94
	v_lshlrev_b32_e32 v94, 16, v95
	v_and_b32_e32 v95, 0xffff0000, v95
	s_mov_b64 s[4:5], 0x50000
	s_waitcnt vmcnt(2)
	v_pk_add_f32 v[94:95], v[192:193], v[94:95]
	s_waitcnt vmcnt(1)
	v_pk_add_f32 v[90:91], v[196:197], v[90:91]
	v_pk_add_f32 v[96:97], v[190:191], v[96:97]
	v_pk_add_f32 v[92:93], v[194:195], v[92:93]
	v_pk_mul_f32 v[192:193], v[198:199], v[94:95]
	v_pk_mul_f32 v[190:191], v[200:201], v[96:97]
	v_pk_mul_f32 v[194:195], v[202:203], v[90:91]
	v_pk_mul_f32 v[196:197], v[204:205], v[92:93]
	v_cvt_pk_bf16_f32 v190, v190, v191
	v_cvt_pk_bf16_f32 v191, v192, v193
	s_nop 0
	v_cvt_pk_bf16_f32 v192, v196, v197
	v_cvt_pk_bf16_f32 v193, v194, v195
	v_lshl_add_u64 v[194:195], s[96:97], 0, v[212:213]
	global_store_dwordx4 v[194:195], v[190:193], off
	s_nop 1
	v_lshl_add_u64 v[192:193], v[184:185], 0, s[4:5]
	v_lshl_add_u64 v[220:221], v[192:193], 0, v[148:149]
	v_lshl_add_u64 v[190:191], v[220:221], 2, s[44:45]
	global_load_dwordx4 v[194:197], v[190:191], off nt
	global_load_dwordx4 v[212:215], v[190:191], off offset:16 nt
	v_lshlrev_b64 v[220:221], 1, v[220:221]
	v_cvt_pk_bf16_f32 v86, v86, v87
	v_cvt_pk_bf16_f32 v87, v88, v89
	v_cvt_pk_bf16_f32 v88, v82, v83
	v_cvt_pk_bf16_f32 v89, v84, v85
	v_lshl_add_u64 v[82:83], s[90:91], 0, v[220:221]
	global_store_dwordx4 v[82:83], v[86:89], off
	v_lshlrev_b32_e32 v84, 16, v88
	v_and_b32_e32 v85, 0xffff0000, v88
	v_lshlrev_b32_e32 v82, 16, v89
	v_and_b32_e32 v83, 0xffff0000, v89
	v_lshlrev_b32_e32 v88, 16, v86
	v_and_b32_e32 v89, 0xffff0000, v86
	v_lshlrev_b32_e32 v86, 16, v87
	v_and_b32_e32 v87, 0xffff0000, v87
	s_mov_b64 s[4:5], 0x58000
	s_waitcnt vmcnt(2)
	v_pk_add_f32 v[86:87], v[196:197], v[86:87]
	s_waitcnt vmcnt(1)
	v_pk_add_f32 v[82:83], v[214:215], v[82:83]
	v_pk_add_f32 v[88:89], v[194:195], v[88:89]
	v_pk_add_f32 v[84:85], v[212:213], v[84:85]
	v_pk_mul_f32 v[196:197], v[198:199], v[86:87]
	v_pk_mul_f32 v[194:195], v[200:201], v[88:89]
	v_pk_mul_f32 v[212:213], v[202:203], v[82:83]
	v_pk_mul_f32 v[214:215], v[204:205], v[84:85]
	v_cvt_pk_bf16_f32 v194, v194, v195
	v_cvt_pk_bf16_f32 v195, v196, v197
	s_nop 0
	v_cvt_pk_bf16_f32 v196, v214, v215
	v_cvt_pk_bf16_f32 v197, v212, v213
	v_lshl_add_u64 v[212:213], s[96:97], 0, v[220:221]
	global_store_dwordx4 v[212:213], v[194:197], off
	s_nop 1
	v_lshl_add_u64 v[196:197], v[184:185], 0, s[4:5]
	v_lshl_add_u64 v[224:225], v[196:197], 0, v[148:149]
	v_lshl_add_u64 v[194:195], v[224:225], 2, s[44:45]
	global_load_dwordx4 v[212:215], v[194:195], off nt
	global_load_dwordx4 v[220:223], v[194:195], off offset:16 nt
	v_lshlrev_b64 v[102:103], 1, v[224:225]
	v_cvt_pk_bf16_f32 v78, v78, v79
	v_cvt_pk_bf16_f32 v79, v80, v81
	v_cvt_pk_bf16_f32 v80, v74, v75
	v_cvt_pk_bf16_f32 v81, v76, v77
	v_lshl_add_u64 v[74:75], s[90:91], 0, v[102:103]
	global_store_dwordx4 v[74:75], v[78:81], off
	v_lshlrev_b32_e32 v76, 16, v80
	v_and_b32_e32 v77, 0xffff0000, v80
	v_lshlrev_b32_e32 v74, 16, v81
	v_and_b32_e32 v75, 0xffff0000, v81
	v_lshlrev_b32_e32 v80, 16, v78
	v_and_b32_e32 v81, 0xffff0000, v78
	v_lshlrev_b32_e32 v78, 16, v79
	v_and_b32_e32 v79, 0xffff0000, v79
	v_lshl_add_u64 v[102:103], s[96:97], 0, v[102:103]
	v_or_b32_e32 v148, 0x80, v148
	s_waitcnt vmcnt(2)
; __device__ __forceinline__ unsigned cvt_pk_bf16(float lo, float hi) { unsigned r; asm volatile("v_cvt_pk_bf16_f32 %0, %1, %2" : "=v"(r) : "v"(lo), "v"(hi)); return r; }
;     __device__ __forceinline__ void operator()(const f32x4 (&acc)[2][2][4][2], const Unit& u, int wr, int wc, int fr, int fq) const {
;     ...
;                 for (int m = 0; m < 4; ++m) { const size_t off = (size_t)(row0 + ai * HALF + m * 16) * 2048 + col0 + bj * HALF;
;                     f32x4 x0 = __builtin_nontemporal_load((const f32x4*)(base + off)), x1 = __builtin_nontemporal_load((const f32x4*)(base + off + 4));
;                     if constexpr (HAS_DIN) { const u32x4 dw = __builtin_nontemporal_load((const u32x4*)(dbuf + off));
;                         x0 += (f32x4){__builtin_bit_cast(float, dw.x << 16), __builtin_bit_cast(float, dw.x & 0xffff0000u), __builtin_bit_cast(float, dw.y << 16), __builtin_bit_cast(float, dw.y & 0xffff0000u)};
;                         x1 += (f32x4){__builtin_bit_cast(float, dw.z << 16), __builtin_bit_cast(float, dw.z & 0xffff0000u), __builtin_bit_cast(float, dw.w << 16), __builtin_bit_cast(float, dw.w & 0xffff0000u)}; }
;                     f32x4 o0, o1;
;                     if constexpr (OUT_DELTA) { const f32x4 d0 = g0 * acc[ai][bj][m][0], d1 = g1 * acc[ai][bj][m][1];
;                         u32x4 w; w.x = cvt_pk_bf16(d0[0], d0[1]); w.y = cvt_pk_bf16(d0[2], d0[3]); w.z = cvt_pk_bf16(d1[0], d1[1]); w.w = cvt_pk_bf16(d1[2], d1[3]);
;                         *(u32x4*)(dbuf + off) = w;
;                         o0 = x0 + (f32x4){__builtin_bit_cast(float, w.x << 16), __builtin_bit_cast(float, w.x & 0xffff0000u), __builtin_bit_cast(float, w.y << 16), __builtin_bit_cast(float, w.y & 0xffff0000u)};
;                         o1 = x1 + (f32x4){__builtin_bit_cast(float, w.z << 16), __builtin_bit_cast(float, w.z & 0xffff0000u), __builtin_bit_cast(float, w.w << 16), __builtin_bit_cast(float, w.w & 0xffff0000u)}; }
;                     else { o0 = x0 + g0 * acc[ai][bj][m][0]; o1 = x1 + g1 * acc[ai][bj][m][1]; *(f32x4*)(out + off) = o0; *(f32x4*)(out + off + 4) = o1; }
;                     if (Hn) { const f32x4 h0 = o0 * G0, h1 = o1 * G1;
;                         u32x4 w; w.x = cvt_pk_bf16(h0[0], h0[1]); w.y = cvt_pk_bf16(h0[2], h0[3]); w.z = cvt_pk_bf16(h1[0], h1[1]); w.w = cvt_pk_bf16(h1[2], h1[3]);
;                         *(u32x4*)(Hn + off) = w;
	v_pk_add_f32 v[78:79], v[214:215], v[78:79]
	v_pk_add_f32 v[80:81], v[212:213], v[80:81]
	s_waitcnt vmcnt(1)
	v_pk_add_f32 v[74:75], v[222:223], v[74:75]
	v_pk_add_f32 v[76:77], v[220:221], v[76:77]
	v_pk_mul_f32 v[100:101], v[198:199], v[78:79]
	v_pk_mul_f32 v[98:99], v[200:201], v[80:81]
	v_pk_mul_f32 v[104:105], v[202:203], v[74:75]
	v_pk_mul_f32 v[198:199], v[204:205], v[76:77]
	v_cvt_pk_bf16_f32 v98, v98, v99
	v_cvt_pk_bf16_f32 v99, v100, v101
	s_nop 0
	v_cvt_pk_bf16_f32 v100, v198, v199
	v_cvt_pk_bf16_f32 v101, v104, v105
	global_store_dwordx4 v[102:103], v[98:101], off
	global_load_dwordx4 v[100:103], v[178:179], off offset:512 nt
	global_load_dwordx4 v[198:201], v[178:179], off offset:528 nt
	v_lshl_add_u64 v[98:99], v[184:185], 0, v[148:149]
	v_pk_mul_f32 v[104:105], v[68:69], v[28:29]
	v_pk_mul_f32 v[68:69], v[66:67], v[26:27]
	v_cvt_pk_bf16_f32 v66, v70, v71
	v_cvt_pk_bf16_f32 v67, v72, v73
	s_nop 0
	v_cvt_pk_bf16_f32 v68, v68, v69
	v_cvt_pk_bf16_f32 v69, v104, v105
	v_lshlrev_b64 v[104:105], 1, v[98:99]
	v_lshl_add_u64 v[70:71], s[90:91], 0, v[104:105]
	global_store_dwordx4 v[70:71], v[66:69], off
	v_lshlrev_b32_e32 v72, 16, v68
	v_and_b32_e32 v73, 0xffff0000, v68
	v_lshlrev_b32_e32 v68, 16, v69
	v_and_b32_e32 v69, 0xffff0000, v69
	s_waitcnt vmcnt(1)
	v_pk_add_f32 v[70:71], v[200:201], v[68:69]
	v_lshlrev_b32_e32 v68, 16, v66
	v_and_b32_e32 v69, 0xffff0000, v66
	v_lshlrev_b32_e32 v66, 16, v67
	v_and_b32_e32 v67, 0xffff0000, v67
	v_pk_add_f32 v[98:99], v[102:103], v[66:67]
	v_pk_add_f32 v[100:101], v[100:101], v[68:69]
	v_pk_add_f32 v[72:73], v[198:199], v[72:73]
	v_pk_mul_f32 v[68:69], v[150:151], v[98:99]
	v_pk_mul_f32 v[66:67], v[152:153], v[100:101]
	v_pk_mul_f32 v[102:103], v[154:155], v[70:71]
	v_pk_mul_f32 v[178:179], v[156:157], v[72:73]
	v_cvt_pk_bf16_f32 v66, v66, v67
	v_cvt_pk_bf16_f32 v67, v68, v69
	s_nop 0
	v_cvt_pk_bf16_f32 v68, v178, v179
	v_cvt_pk_bf16_f32 v69, v102, v103
	v_lshl_add_u64 v[102:103], s[96:97], 0, v[104:105]
	global_store_dwordx4 v[102:103], v[66:69], off
	s_nop 1
	v_mul_f32_e32 v66, v101, v101
	v_mul_f32_e32 v67, v99, v99
	v_fmac_f32_e32 v66, v100, v100
	v_fmac_f32_e32 v67, v98, v98
	v_add_f32_e32 v66, v66, v67
	v_mul_f32_e32 v67, v73, v73
	v_mul_f32_e32 v68, v71, v71
	v_fmac_f32_e32 v67, v72, v72
	v_fmac_f32_e32 v68, v70, v70
	v_add_f32_e32 v67, v67, v68
	global_load_dwordx4 v[68:71], v[138:139], off offset:512 nt
	global_load_dwordx4 v[98:101], v[138:139], off offset:528 nt
	v_lshl_add_u64 v[72:73], v[140:141], 0, v[148:149]
	v_lshlrev_b64 v[72:73], 1, v[72:73]
	v_cvt_pk_bf16_f32 v62, v62, v63
	v_cvt_pk_bf16_f32 v63, v64, v65
	v_cvt_pk_bf16_f32 v64, v58, v59
	v_cvt_pk_bf16_f32 v65, v60, v61
	v_lshl_add_u64 v[58:59], s[90:91], 0, v[72:73]
	global_store_dwordx4 v[58:59], v[62:65], off
	v_lshlrev_b32_e32 v60, 16, v64
	v_and_b32_e32 v61, 0xffff0000, v64
	v_lshlrev_b32_e32 v58, 16, v65
	v_and_b32_e32 v59, 0xffff0000, v65
	v_lshlrev_b32_e32 v64, 16, v62
	v_and_b32_e32 v65, 0xffff0000, v62
	v_lshlrev_b32_e32 v62, 16, v63
	v_and_b32_e32 v63, 0xffff0000, v63
	v_lshl_add_u64 v[72:73], s[96:97], 0, v[72:73]
	v_add_f32_e32 v66, v66, v67
	v_add_f32_e32 v66, v211, v66
	s_waitcnt vmcnt(2)
	v_pk_add_f32 v[62:63], v[70:71], v[62:63]
	v_pk_add_f32 v[64:65], v[68:69], v[64:65]
	s_waitcnt vmcnt(1)
	v_pk_add_f32 v[58:59], v[100:101], v[58:59]
	v_pk_add_f32 v[60:61], v[98:99], v[60:61]
	v_pk_mul_f32 v[70:71], v[150:151], v[62:63]
	v_pk_mul_f32 v[68:69], v[152:153], v[64:65]
	v_pk_mul_f32 v[98:99], v[154:155], v[58:59]
	v_pk_mul_f32 v[100:101], v[156:157], v[60:61]
	v_cvt_pk_bf16_f32 v68, v68, v69
	v_cvt_pk_bf16_f32 v69, v70, v71
	s_nop 0
	v_cvt_pk_bf16_f32 v70, v100, v101
	v_cvt_pk_bf16_f32 v71, v98, v99
	global_store_dwordx4 v[72:73], v[68:71], off
	global_load_dwordx4 v[68:71], v[142:143], off offset:512 nt
	s_nop 0
	global_load_dwordx4 v[98:101], v[142:143], off offset:528 nt
	v_lshl_add_u64 v[72:73], v[144:145], 0, v[148:149]
	v_lshlrev_b64 v[72:73], 1, v[72:73]
	v_cvt_pk_bf16_f32 v54, v54, v55
	v_cvt_pk_bf16_f32 v55, v56, v57
	v_cvt_pk_bf16_f32 v56, v50, v51
	v_cvt_pk_bf16_f32 v57, v52, v53
	v_lshl_add_u64 v[50:51], s[90:91], 0, v[72:73]
	global_store_dwordx4 v[50:51], v[54:57], off
	v_lshlrev_b32_e32 v52, 16, v56
	v_and_b32_e32 v53, 0xffff0000, v56
	v_lshlrev_b32_e32 v50, 16, v57
	v_and_b32_e32 v51, 0xffff0000, v57
	v_lshlrev_b32_e32 v56, 16, v54
	v_and_b32_e32 v57, 0xffff0000, v54
	v_lshlrev_b32_e32 v54, 16, v55
	v_and_b32_e32 v55, 0xffff0000, v55
	v_lshl_add_u64 v[72:73], s[96:97], 0, v[72:73]
	s_waitcnt vmcnt(2)
	v_pk_add_f32 v[54:55], v[70:71], v[54:55]
	v_pk_add_f32 v[56:57], v[68:69], v[56:57]
	s_waitcnt vmcnt(1)
	v_pk_add_f32 v[50:51], v[100:101], v[50:51]
	v_pk_add_f32 v[52:53], v[98:99], v[52:53]
	v_pk_mul_f32 v[70:71], v[150:151], v[54:55]
	v_pk_mul_f32 v[68:69], v[152:153], v[56:57]
	v_pk_mul_f32 v[98:99], v[154:155], v[50:51]
	v_pk_mul_f32 v[100:101], v[156:157], v[52:53]
	v_cvt_pk_bf16_f32 v68, v68, v69
	v_cvt_pk_bf16_f32 v69, v70, v71
	s_nop 0
	v_cvt_pk_bf16_f32 v70, v100, v101
	v_cvt_pk_bf16_f32 v71, v98, v99
	global_store_dwordx4 v[72:73], v[68:71], off
	global_load_dwordx4 v[68:71], v[158:159], off offset:512 nt
	s_nop 0
	global_load_dwordx4 v[98:101], v[158:159], off offset:528 nt
	v_lshl_add_u64 v[72:73], v[160:161], 0, v[148:149]
	v_lshlrev_b64 v[72:73], 1, v[72:73]
	v_cvt_pk_bf16_f32 v46, v46, v47
	v_cvt_pk_bf16_f32 v47, v48, v49
	v_cvt_pk_bf16_f32 v48, v42, v43
	v_cvt_pk_bf16_f32 v49, v44, v45
	v_lshl_add_u64 v[42:43], s[90:91], 0, v[72:73]
	global_store_dwordx4 v[42:43], v[46:49], off
	v_lshlrev_b32_e32 v44, 16, v48
	v_and_b32_e32 v45, 0xffff0000, v48
	v_lshlrev_b32_e32 v42, 16, v49
	v_and_b32_e32 v43, 0xffff0000, v49
	v_lshlrev_b32_e32 v48, 16, v46
	v_and_b32_e32 v49, 0xffff0000, v46
	v_lshlrev_b32_e32 v46, 16, v47
	v_and_b32_e32 v47, 0xffff0000, v47
	v_lshl_add_u64 v[72:73], s[96:97], 0, v[72:73]
	s_waitcnt vmcnt(2)
; __device__ __forceinline__ unsigned cvt_pk_bf16(float lo, float hi) { unsigned r; asm volatile("v_cvt_pk_bf16_f32 %0, %1, %2" : "=v"(r) : "v"(lo), "v"(hi)); return r; }
;     __device__ __forceinline__ void operator()(const f32x4 (&acc)[2][2][4][2], const Unit& u, int wr, int wc, int fr, int fq) const {
;     ...
;                 for (int m = 0; m < 4; ++m) { const size_t off = (size_t)(row0 + ai * HALF + m * 16) * 2048 + col0 + bj * HALF;
;                     f32x4 x0 = __builtin_nontemporal_load((const f32x4*)(base + off)), x1 = __builtin_nontemporal_load((const f32x4*)(base + off + 4));
;                     if constexpr (HAS_DIN) { const u32x4 dw = __builtin_nontemporal_load((const u32x4*)(dbuf + off));
;                         x0 += (f32x4){__builtin_bit_cast(float, dw.x << 16), __builtin_bit_cast(float, dw.x & 0xffff0000u), __builtin_bit_cast(float, dw.y << 16), __builtin_bit_cast(float, dw.y & 0xffff0000u)};
;                         x1 += (f32x4){__builtin_bit_cast(float, dw.z << 16), __builtin_bit_cast(float, dw.z & 0xffff0000u), __builtin_bit_cast(float, dw.w << 16), __builtin_bit_cast(float, dw.w & 0xffff0000u)}; }
;                     f32x4 o0, o1;
;                     if constexpr (OUT_DELTA) { const f32x4 d0 = g0 * acc[ai][bj][m][0], d1 = g1 * acc[ai][bj][m][1];
;                         u32x4 w; w.x = cvt_pk_bf16(d0[0], d0[1]); w.y = cvt_pk_bf16(d0[2], d0[3]); w.z = cvt_pk_bf16(d1[0], d1[1]); w.w = cvt_pk_bf16(d1[2], d1[3]);
;                         *(u32x4*)(dbuf + off) = w;
;                         o0 = x0 + (f32x4){__builtin_bit_cast(float, w.x << 16), __builtin_bit_cast(float, w.x & 0xffff0000u), __builtin_bit_cast(float, w.y << 16), __builtin_bit_cast(float, w.y & 0xffff0000u)};
;                         o1 = x1 + (f32x4){__builtin_bit_cast(float, w.z << 16), __builtin_bit_cast(float, w.z & 0xffff0000u), __builtin_bit_cast(float, w.w << 16), __builtin_bit_cast(float, w.w & 0xffff0000u)}; }
;                     else { o0 = x0 + g0 * acc[ai][bj][m][0]; o1 = x1 + g1 * acc[ai][bj][m][1]; *(f32x4*)(out + off) = o0; *(f32x4*)(out + off + 4) = o1; }
;                     if (Hn) { const f32x4 h0 = o0 * G0, h1 = o1 * G1;
;                         u32x4 w; w.x = cvt_pk_bf16(h0[0], h0[1]); w.y = cvt_pk_bf16(h0[2], h0[3]); w.z = cvt_pk_bf16(h1[0], h1[1]); w.w = cvt_pk_bf16(h1[2], h1[3]);
;                         *(u32x4*)(Hn + off) = w;
	v_pk_add_f32 v[46:47], v[70:71], v[46:47]
	v_pk_add_f32 v[48:49], v[68:69], v[48:49]
	s_waitcnt vmcnt(1)
	v_pk_add_f32 v[42:43], v[100:101], v[42:43]
	v_pk_add_f32 v[44:45], v[98:99], v[44:45]
	v_pk_mul_f32 v[70:71], v[150:151], v[46:47]
	v_pk_mul_f32 v[68:69], v[152:153], v[48:49]
	v_pk_mul_f32 v[98:99], v[154:155], v[42:43]
	v_pk_mul_f32 v[100:101], v[156:157], v[44:45]
	v_cvt_pk_bf16_f32 v68, v68, v69
	v_cvt_pk_bf16_f32 v69, v70, v71
	s_nop 0
	v_cvt_pk_bf16_f32 v70, v100, v101
	v_cvt_pk_bf16_f32 v71, v98, v99
	global_store_dwordx4 v[72:73], v[68:71], off
	global_load_dwordx4 v[68:71], v[180:181], off offset:512 nt
	s_nop 0
	global_load_dwordx4 v[98:101], v[180:181], off offset:528 nt
	v_lshl_add_u64 v[72:73], v[182:183], 0, v[148:149]
	v_lshlrev_b64 v[72:73], 1, v[72:73]
	v_cvt_pk_bf16_f32 v38, v38, v39
	v_cvt_pk_bf16_f32 v39, v40, v41
	v_cvt_pk_bf16_f32 v40, v34, v35
	v_cvt_pk_bf16_f32 v41, v36, v37
	v_lshl_add_u64 v[34:35], s[90:91], 0, v[72:73]
	global_store_dwordx4 v[34:35], v[38:41], off
	v_lshlrev_b32_e32 v36, 16, v40
	v_and_b32_e32 v37, 0xffff0000, v40
	v_lshlrev_b32_e32 v34, 16, v41
	v_and_b32_e32 v35, 0xffff0000, v41
	v_lshlrev_b32_e32 v40, 16, v38
	v_and_b32_e32 v41, 0xffff0000, v38
	v_lshlrev_b32_e32 v38, 16, v39
	v_and_b32_e32 v39, 0xffff0000, v39
	v_lshl_add_u64 v[72:73], s[96:97], 0, v[72:73]
	s_waitcnt vmcnt(2)
	v_pk_add_f32 v[38:39], v[70:71], v[38:39]
	v_pk_add_f32 v[40:41], v[68:69], v[40:41]
	s_waitcnt vmcnt(1)
	v_pk_add_f32 v[34:35], v[100:101], v[34:35]
	v_pk_add_f32 v[36:37], v[98:99], v[36:37]
	v_pk_mul_f32 v[70:71], v[150:151], v[38:39]
	v_pk_mul_f32 v[68:69], v[152:153], v[40:41]
	v_pk_mul_f32 v[98:99], v[154:155], v[34:35]
	v_pk_mul_f32 v[100:101], v[156:157], v[36:37]
	v_cvt_pk_bf16_f32 v68, v68, v69
	v_cvt_pk_bf16_f32 v69, v70, v71
	s_nop 0
	v_cvt_pk_bf16_f32 v70, v100, v101
	v_cvt_pk_bf16_f32 v71, v98, v99
	global_store_dwordx4 v[72:73], v[68:71], off
	global_load_dwordx4 v[68:71], v[186:187], off offset:512 nt
	s_nop 0
	global_load_dwordx4 v[98:101], v[186:187], off offset:528 nt
	v_lshl_add_u64 v[72:73], v[188:189], 0, v[148:149]
	v_lshlrev_b64 v[72:73], 1, v[72:73]
	v_cvt_pk_bf16_f32 v22, v22, v23
	v_cvt_pk_bf16_f32 v23, v24, v25
	v_cvt_pk_bf16_f32 v24, v18, v19
	v_cvt_pk_bf16_f32 v25, v20, v21
	v_lshl_add_u64 v[18:19], s[90:91], 0, v[72:73]
	global_store_dwordx4 v[18:19], v[22:25], off
	v_lshlrev_b32_e32 v20, 16, v24
	v_and_b32_e32 v21, 0xffff0000, v24
	v_lshlrev_b32_e32 v18, 16, v25
	v_and_b32_e32 v19, 0xffff0000, v25
	v_lshlrev_b32_e32 v24, 16, v22
	v_and_b32_e32 v25, 0xffff0000, v22
	v_lshlrev_b32_e32 v22, 16, v23
	v_and_b32_e32 v23, 0xffff0000, v23
	v_lshl_add_u64 v[72:73], s[96:97], 0, v[72:73]
	s_waitcnt vmcnt(2)
	v_pk_add_f32 v[22:23], v[70:71], v[22:23]
	v_pk_add_f32 v[24:25], v[68:69], v[24:25]
	s_waitcnt vmcnt(1)
	v_pk_add_f32 v[18:19], v[100:101], v[18:19]
	v_pk_add_f32 v[20:21], v[98:99], v[20:21]
	v_pk_mul_f32 v[70:71], v[150:151], v[22:23]
	v_pk_mul_f32 v[68:69], v[152:153], v[24:25]
	v_pk_mul_f32 v[98:99], v[154:155], v[18:19]
	v_pk_mul_f32 v[100:101], v[156:157], v[20:21]
	v_cvt_pk_bf16_f32 v68, v68, v69
	v_cvt_pk_bf16_f32 v69, v70, v71
	s_nop 0
	v_cvt_pk_bf16_f32 v70, v100, v101
	v_cvt_pk_bf16_f32 v71, v98, v99
	global_store_dwordx4 v[72:73], v[68:71], off
	global_load_dwordx4 v[68:71], v[190:191], off offset:512 nt
	s_nop 0
	global_load_dwordx4 v[98:101], v[190:191], off offset:528 nt
	v_lshl_add_u64 v[72:73], v[192:193], 0, v[148:149]
	v_lshlrev_b64 v[72:73], 1, v[72:73]
	v_cvt_pk_bf16_f32 v14, v14, v15
	v_cvt_pk_bf16_f32 v15, v16, v17
	v_cvt_pk_bf16_f32 v16, v10, v11
	v_cvt_pk_bf16_f32 v17, v12, v13
	v_lshl_add_u64 v[10:11], s[90:91], 0, v[72:73]
	global_store_dwordx4 v[10:11], v[14:17], off
	v_lshlrev_b32_e32 v12, 16, v16
	v_and_b32_e32 v13, 0xffff0000, v16
	v_lshlrev_b32_e32 v10, 16, v17
	v_and_b32_e32 v11, 0xffff0000, v17
	v_lshlrev_b32_e32 v16, 16, v14
	v_and_b32_e32 v17, 0xffff0000, v14
	v_lshlrev_b32_e32 v14, 16, v15
	v_and_b32_e32 v15, 0xffff0000, v15
	v_lshl_add_u64 v[72:73], s[96:97], 0, v[72:73]
	s_waitcnt vmcnt(2)
	v_pk_add_f32 v[14:15], v[70:71], v[14:15]
	v_pk_add_f32 v[16:17], v[68:69], v[16:17]
	s_waitcnt vmcnt(1)
	v_pk_add_f32 v[10:11], v[100:101], v[10:11]
	v_pk_add_f32 v[12:13], v[98:99], v[12:13]
	v_pk_mul_f32 v[70:71], v[150:151], v[14:15]
	v_pk_mul_f32 v[68:69], v[152:153], v[16:17]
	v_pk_mul_f32 v[98:99], v[154:155], v[10:11]
	v_pk_mul_f32 v[100:101], v[156:157], v[12:13]
	v_cvt_pk_bf16_f32 v68, v68, v69
	v_cvt_pk_bf16_f32 v69, v70, v71
	s_nop 0
	v_cvt_pk_bf16_f32 v70, v100, v101
	v_cvt_pk_bf16_f32 v71, v98, v99
	global_store_dwordx4 v[72:73], v[68:71], off
	global_load_dwordx4 v[68:71], v[194:195], off offset:512 nt
	s_nop 0
	global_load_dwordx4 v[98:101], v[194:195], off offset:528 nt
	v_lshl_add_u64 v[72:73], v[196:197], 0, v[148:149]
	v_lshlrev_b64 v[30:31], 1, v[72:73]
	v_cvt_pk_bf16_f32 v6, v6, v7
	v_cvt_pk_bf16_f32 v7, v8, v9
	v_cvt_pk_bf16_f32 v8, v2, v3
	v_cvt_pk_bf16_f32 v9, v4, v5
	v_lshl_add_u64 v[2:3], s[90:91], 0, v[30:31]
	global_store_dwordx4 v[2:3], v[6:9], off
	v_lshlrev_b32_e32 v4, 16, v8
	v_and_b32_e32 v5, 0xffff0000, v8
	v_lshlrev_b32_e32 v2, 16, v9
	v_and_b32_e32 v3, 0xffff0000, v9
	v_lshlrev_b32_e32 v8, 16, v6
	v_and_b32_e32 v9, 0xffff0000, v6
	v_lshlrev_b32_e32 v6, 16, v7
	v_and_b32_e32 v7, 0xffff0000, v7
	v_lshl_add_u64 v[30:31], s[96:97], 0, v[30:31]
	s_waitcnt vmcnt(2)
	v_pk_add_f32 v[8:9], v[68:69], v[8:9]
	v_pk_add_f32 v[6:7], v[70:71], v[6:7]
	v_pk_mul_f32 v[26:27], v[152:153], v[8:9]
	s_waitcnt vmcnt(1)
	v_pk_add_f32 v[2:3], v[100:101], v[2:3]
	v_pk_add_f32 v[4:5], v[98:99], v[4:5]
	v_pk_mul_f32 v[28:29], v[150:151], v[6:7]
	v_cvt_pk_bf16_f32 v26, v26, v27
	v_pk_mul_f32 v[32:33], v[154:155], v[2:3]
	v_cvt_pk_bf16_f32 v27, v28, v29
	v_pk_mul_f32 v[68:69], v[156:157], v[4:5]
	s_nop 0
	v_cvt_pk_bf16_f32 v28, v68, v69
	v_cvt_pk_bf16_f32 v29, v32, v33
	global_store_dwordx4 v[30:31], v[26:29], off
	s_nop 1
	v_and_b32_e32 v27, 64, v218
	v_xor_b32_e32 v26, 16, v218
	v_add_u32_e32 v27, 64, v27
	v_cmp_lt_i32_e32 vcc, v26, v27
	s_nop 1
	v_cndmask_b32_e32 v26, v218, v26, vcc
	v_lshlrev_b32_e32 v28, 2, v26
	v_xor_b32_e32 v26, 32, v218
	v_cmp_lt_i32_e32 vcc, v26, v27
	s_nop 1
	v_cndmask_b32_e32 v26, v218, v26, vcc
	v_lshlrev_b32_e32 v29, 2, v26
	ds_bpermute_b32 v26, v28, v66
	s_waitcnt lgkmcnt(0)
	v_add_f32_e32 v30, v66, v26
	ds_bpermute_b32 v31, v29, v30
	v_lshl_add_u64 v[26:27], v[146:147], 3, s[42:43]
	s_and_saveexec_b64 s[4:5], s[0:1]
	s_mov_b32 s8, 0x2f800000
	s_mov_b32 s9, 0xcf800000
	s_cbranch_execz .LBB0_558
	s_waitcnt lgkmcnt(0)
	v_add_f32_e32 v30, v30, v31
	v_mul_f32_e32 v30, 0x47800000, v30
	v_rndne_f32_e32 v30, v30
	v_mul_f32_e64 v31, |v30|, s8
	v_floor_f32_e32 v31, v31
	v_fma_f32 v32, v31, s9, |v30|
	v_cvt_u32_f32_e32 v32, v32
	v_cvt_u32_f32_e32 v31, v31
	v_ashrrev_i32_e32 v33, 31, v30
	v_xor_b32_e32 v30, v32, v33
	v_xor_b32_e32 v31, v31, v33
	v_sub_co_u32_e32 v30, vcc, v30, v33
	s_nop 1
	v_subb_co_u32_e32 v31, vcc, v31, v33, vcc
	global_atomic_add_x2 v[26:27], v[30:31], off

; #define PG8_STAGE(bufoff, gbase, voff) do { const char* gb_ = (const char*)(gbase); asm volatile("" : "+s"(gb_)); _Pragma("unroll") for (int _i = 0; _i < 2; ++_i) { unsigned vo_ = (voff)[_i]; asm volatile("" : "+v"(vo_));        \
;         __builtin_amdgcn_global_load_lds((const unsigned*)(gb_ + vo_), (PG8_LAS unsigned*)(lds + (bufoff) + ldsw + _i * 8192), 16, 0, 0); } } while (0)
; #define PG8_LDA(dst, b, h) do { _Pragma("unroll") for (int m = 0; m < 4; ++m) _Pragma("unroll") for (int k = 0; k < 2; ++k) dst[m][k] = *(const PG8_LAS bf16x8*)(lds + PG8_SA(b, h) + aoff + m * 2048 + k * 1024); } while (0)
; #define PG8_LDB(dst, b, h) do { _Pragma("unroll") for (int n = 0; n < 2; ++n) _Pragma("unroll") for (int k = 0; k < 2; ++k) dst[n][k] = *(const PG8_LAS bf16x8*)(lds + PG8_SB(b, h) + boff + n * 2048 + k * 1024); } while (0)
; #define PG8_MMA(ai, bj, At, Bt) do { __builtin_amdgcn_s_setprio(1); _Pragma("unroll") for (int m = 0; m < 4; ++m) _Pragma("unroll") for (int n = 0; n < 2; ++n) _Pragma("unroll") for (int k = 0; k < 2; ++k) \
;         acc[ai][bj][m][n] = __builtin_amdgcn_mfma_f32_16x16x32_bf16(Bt[n][k], At[m][k], acc[ai][bj][m][n], 0, 0, 0); __builtin_amdgcn_s_setprio(0); } while (0)
; template <class Epi, class Sched, bool ALIGN_EPI = false, bool SP2 = false>
; __device__ __forceinline__ void gemm_phase(PG8_LAS unsigned char* lds, const Gemm g, const Sched& S, const Epi& E) {
;     ...
;         for (int t = 0; t < nt; t += 2) {
;             const bool last = (t == nt - 2);
;             const char* a1 = cA + (size_t)(t + 1) * kstep;
;             const char* a2 = last ? nA : cA + (size_t)(t + 2) * kstep; const char* b2 = last ? nB : cB + (size_t)(t + 2) * kstep;
;             const char* a3 = a2 + kstep; const char* b3 = b2 + kstep;
;             if (last && has_next) S.a_ready(nxt);
;             if constexpr (SP2) {
;             PG8_LDB(B0, 0, 0); PG8_LDB(B1, 0, 1); PG8_SCHED; PG8_LDA(At, 0, 0); PG8_STAGE(PG8_SA(1, 1), a1 + hstep, voffA);
;             PG8_WAIT_V(8); PG8_WAIT_L(0); PG8_BAR; PG8_MMA(0, 0, At, B0); PG8_MMA(0, 1, At, B1); PG8_BAR; PG8_SCHED;
;             PG8_LDA(At, 0, 1); PG8_STAGE(PG8_SB(0, 0), b2, voffB); PG8_STAGE(PG8_SB(0, 1), b2 + hstep, voffB); PG8_STAGE(PG8_SA(0, 0), a2, voffA);
;             PG8_WAIT_V(8); PG8_WAIT_L(0); PG8_BAR; PG8_MMA(1, 0, At, B0); PG8_MMA(1, 1, At, B1); PG8_BAR; PG8_SCHED;
.LBB0_634:
	s_add_u32 s16, s14, 0x100
	s_addc_u32 s17, s15, 0
	s_cmp_eq_u32 s53, 28
	s_cselect_b32 s22, s49, s16
	s_cselect_b32 s23, s7, s17
	s_cselect_b32 s20, s50, s51
	s_cselect_b32 s21, s5, s52
	s_add_u32 s18, s22, 0x80
	s_addc_u32 s19, s23, 0
	s_add_i32 s54, 0, 0x10000
	s_add_i32 s55, 0, 0x14000
	ds_read_b128 v[82:85], v244
	ds_read_b128 v[86:89], v244 offset:1024
	ds_read_b128 v[90:93], v244 offset:2048
	ds_read_b128 v[94:97], v244 offset:3072
	ds_read_b128 v[146:149], v244 offset:16384
	ds_read_b128 v[150:153], v244 offset:17408
	ds_read_b128 v[154:157], v244 offset:18432
	ds_read_b128 v[158:161], v244 offset:19456
	s_add_u32 s14, s14, 0x80080
	s_addc_u32 s15, s15, 0
	ds_read_b128 v[178:181], v188
	ds_read_b128 v[190:193], v188 offset:1024
	ds_read_b128 v[194:197], v188 offset:2048
	ds_read_b128 v[198:201], v188 offset:3072
	ds_read_b128 v[202:205], v188 offset:4096
	ds_read_b128 v[206:209], v188 offset:5120
	ds_read_b128 v[210:213], v188 offset:6144
	ds_read_b128 v[220:223], v188 offset:7168
	s_add_i32 m0, s27, 0xc000
	s_nop 0
	global_load_lds_dwordx4 v1, s[14:15]
	s_add_i32 m0, s27, 0xe000
	s_nop 0
	global_load_lds_dwordx4 v164, s[14:15]
	s_waitcnt vmcnt(8)
	s_waitcnt lgkmcnt(0)
	s_barrier
	s_waitcnt lgkmcnt(0)
	v_mfma_f32_16x16x32_bf16 v[142:145], v[82:85], v[178:181], v[142:145]
	v_mfma_f32_16x16x32_bf16 v[142:145], v[86:89], v[190:193], v[142:145]
	v_mfma_f32_16x16x32_bf16 v[126:129], v[82:85], v[194:197], v[126:129]
	v_mfma_f32_16x16x32_bf16 v[126:129], v[86:89], v[198:201], v[126:129]
	v_mfma_f32_16x16x32_bf16 v[110:113], v[82:85], v[202:205], v[110:113]
	v_mfma_f32_16x16x32_bf16 v[110:113], v[86:89], v[206:209], v[110:113]
	v_mfma_f32_16x16x32_bf16 v[78:81], v[82:85], v[210:213], v[78:81]
	v_mfma_f32_16x16x32_bf16 v[78:81], v[86:89], v[220:223], v[78:81]
	v_mfma_f32_16x16x32_bf16 v[138:141], v[90:93], v[178:181], v[138:141]
	v_mfma_f32_16x16x32_bf16 v[138:141], v[94:97], v[190:193], v[138:141]
	v_mfma_f32_16x16x32_bf16 v[122:125], v[90:93], v[194:197], v[122:125]
	v_mfma_f32_16x16x32_bf16 v[122:125], v[94:97], v[198:201], v[122:125]
	v_mfma_f32_16x16x32_bf16 v[106:109], v[90:93], v[202:205], v[106:109]
	v_mfma_f32_16x16x32_bf16 v[106:109], v[94:97], v[206:209], v[106:109]
	v_mfma_f32_16x16x32_bf16 v[74:77], v[90:93], v[210:213], v[74:77]
	v_mfma_f32_16x16x32_bf16 v[74:77], v[94:97], v[220:223], v[74:77]
	v_mfma_f32_16x16x32_bf16 v[134:137], v[146:149], v[178:181], v[134:137]
	v_mfma_f32_16x16x32_bf16 v[134:137], v[150:153], v[190:193], v[134:137]
	v_mfma_f32_16x16x32_bf16 v[118:121], v[146:149], v[194:197], v[118:121]
	v_mfma_f32_16x16x32_bf16 v[118:121], v[150:153], v[198:201], v[118:121]
	v_mfma_f32_16x16x32_bf16 v[102:105], v[146:149], v[202:205], v[102:105]
	v_mfma_f32_16x16x32_bf16 v[102:105], v[150:153], v[206:209], v[102:105]
	v_mfma_f32_16x16x32_bf16 v[70:73], v[146:149], v[210:213], v[70:73]
	v_mfma_f32_16x16x32_bf16 v[70:73], v[150:153], v[220:223], v[70:73]
	v_mfma_f32_16x16x32_bf16 v[130:133], v[154:157], v[178:181], v[130:133]
	v_mfma_f32_16x16x32_bf16 v[130:133], v[158:161], v[190:193], v[130:133]
	v_mfma_f32_16x16x32_bf16 v[114:117], v[154:157], v[194:197], v[114:117]
	v_mfma_f32_16x16x32_bf16 v[114:117], v[158:161], v[198:201], v[114:117]
	v_mfma_f32_16x16x32_bf16 v[98:101], v[154:157], v[202:205], v[98:101]
	v_mfma_f32_16x16x32_bf16 v[98:101], v[158:161], v[206:209], v[98:101]
	v_mfma_f32_16x16x32_bf16 v[66:69], v[154:157], v[210:213], v[66:69]
	v_mfma_f32_16x16x32_bf16 v[66:69], v[158:161], v[220:223], v[66:69]
	s_barrier
	s_mov_b64 s[14:15], s[20:21]
	s_add_i32 s54, s54, s26
	ds_read_b128 v[178:181], v188 offset:16384
	ds_read_b128 v[190:193], v188 offset:17408
	ds_read_b128 v[194:197], v188 offset:18432
	ds_read_b128 v[198:201], v188 offset:19456
	ds_read_b128 v[202:205], v188 offset:20480
	ds_read_b128 v[206:209], v188 offset:21504
	ds_read_b128 v[210:213], v188 offset:22528
	ds_read_b128 v[220:223], v188 offset:23552
	s_mov_b32 m0, s54
	s_nop 0
	global_load_lds_dwordx4 v162, s[14:15]
	s_add_i32 m0, s54, 0x2000
	s_nop 0
	global_load_lds_dwordx4 v184, s[14:15]
	s_add_u32 s14, s20, 0x80000
	s_addc_u32 s15, s21, 0
	s_add_i32 s54, s55, s26
	s_mov_b32 m0, s54
	s_nop 0
	global_load_lds_dwordx4 v162, s[14:15]
	s_add_i32 m0, s54, 0x2000
	s_nop 0
	global_load_lds_dwordx4 v184, s[14:15]
	s_mov_b64 s[14:15], s[22:23]
	s_mov_b32 m0, s27
	s_nop 0
	global_load_lds_dwordx4 v1, s[14:15]
	s_mov_b32 m0, s28
	s_nop 0
	global_load_lds_dwordx4 v164, s[14:15]
	s_waitcnt vmcnt(8)
	s_waitcnt lgkmcnt(0)
	s_barrier
	s_waitcnt lgkmcnt(0)
	v_mfma_f32_16x16x32_bf16 v[62:65], v[82:85], v[178:181], v[62:65]
	v_mfma_f32_16x16x32_bf16 v[62:65], v[86:89], v[190:193], v[62:65]
	v_mfma_f32_16x16x32_bf16 v[46:49], v[82:85], v[194:197], v[46:49]
	v_mfma_f32_16x16x32_bf16 v[46:49], v[86:89], v[198:201], v[46:49]
	v_mfma_f32_16x16x32_bf16 v[30:33], v[82:85], v[202:205], v[30:33]
	v_mfma_f32_16x16x32_bf16 v[30:33], v[86:89], v[206:209], v[30:33]
	v_mfma_f32_16x16x32_bf16 v[14:17], v[82:85], v[210:213], v[14:17]
	v_mfma_f32_16x16x32_bf16 v[14:17], v[86:89], v[220:223], v[14:17]
	v_mfma_f32_16x16x32_bf16 v[58:61], v[90:93], v[178:181], v[58:61]
	v_mfma_f32_16x16x32_bf16 v[58:61], v[94:97], v[190:193], v[58:61]
	v_mfma_f32_16x16x32_bf16 v[42:45], v[90:93], v[194:197], v[42:45]
	v_mfma_f32_16x16x32_bf16 v[42:45], v[94:97], v[198:201], v[42:45]
	v_mfma_f32_16x16x32_bf16 v[26:29], v[90:93], v[202:205], v[26:29]
	v_mfma_f32_16x16x32_bf16 v[26:29], v[94:97], v[206:209], v[26:29]
	v_mfma_f32_16x16x32_bf16 v[10:13], v[90:93], v[210:213], v[10:13]
	v_mfma_f32_16x16x32_bf16 v[10:13], v[94:97], v[220:223], v[10:13]
	v_mfma_f32_16x16x32_bf16 v[54:57], v[146:149], v[178:181], v[54:57]
	v_mfma_f32_16x16x32_bf16 v[54:57], v[150:153], v[190:193], v[54:57]
	v_mfma_f32_16x16x32_bf16 v[38:41], v[146:149], v[194:197], v[38:41]
	v_mfma_f32_16x16x32_bf16 v[38:41], v[150:153], v[198:201], v[38:41]
	v_mfma_f32_16x16x32_bf16 v[22:25], v[146:149], v[202:205], v[22:25]
	v_mfma_f32_16x16x32_bf16 v[22:25], v[150:153], v[206:209], v[22:25]
	v_mfma_f32_16x16x32_bf16 v[6:9], v[146:149], v[210:213], v[6:9]
	v_mfma_f32_16x16x32_bf16 v[6:9], v[150:153], v[220:223], v[6:9]
	v_mfma_f32_16x16x32_bf16 v[50:53], v[154:157], v[178:181], v[50:53]
	v_mfma_f32_16x16x32_bf16 v[50:53], v[158:161], v[190:193], v[50:53]
	v_mfma_f32_16x16x32_bf16 v[34:37], v[154:157], v[194:197], v[34:37]
	v_mfma_f32_16x16x32_bf16 v[34:37], v[158:161], v[198:201], v[34:37]
	v_mfma_f32_16x16x32_bf16 v[18:21], v[154:157], v[202:205], v[18:21]
	v_mfma_f32_16x16x32_bf16 v[18:21], v[158:161], v[206:209], v[18:21]
	v_mfma_f32_16x16x32_bf16 v[2:5], v[154:157], v[210:213], v[2:5]
	v_mfma_f32_16x16x32_bf16 v[2:5], v[158:161], v[220:223], v[2:5]
	s_barrier
; #define PG8_STAGE(bufoff, gbase, voff) do { const char* gb_ = (const char*)(gbase); asm volatile("" : "+s"(gb_)); _Pragma("unroll") for (int _i = 0; _i < 2; ++_i) { unsigned vo_ = (voff)[_i]; asm volatile("" : "+v"(vo_));        \
;         __builtin_amdgcn_global_load_lds((const unsigned*)(gb_ + vo_), (PG8_LAS unsigned*)(lds + (bufoff) + ldsw + _i * 8192), 16, 0, 0); } } while (0)
; #define PG8_LDA(dst, b, h) do { _Pragma("unroll") for (int m = 0; m < 4; ++m) _Pragma("unroll") for (int k = 0; k < 2; ++k) dst[m][k] = *(const PG8_LAS bf16x8*)(lds + PG8_SA(b, h) + aoff + m * 2048 + k * 1024); } while (0)
; #define PG8_LDB(dst, b, h) do { _Pragma("unroll") for (int n = 0; n < 2; ++n) _Pragma("unroll") for (int k = 0; k < 2; ++k) dst[n][k] = *(const PG8_LAS bf16x8*)(lds + PG8_SB(b, h) + boff + n * 2048 + k * 1024); } while (0)
; #define PG8_MMA(ai, bj, At, Bt) do { __builtin_amdgcn_s_setprio(1); _Pragma("unroll") for (int m = 0; m < 4; ++m) _Pragma("unroll") for (int n = 0; n < 2; ++n) _Pragma("unroll") for (int k = 0; k < 2; ++k) \
;         acc[ai][bj][m][n] = __builtin_amdgcn_mfma_f32_16x16x32_bf16(Bt[n][k], At[m][k], acc[ai][bj][m][n], 0, 0, 0); __builtin_amdgcn_s_setprio(0); } while (0)
; #define PG8_WAIT_V(n) asm volatile("s_waitcnt vmcnt(" #n ")" ::: "memory")
; #define PG8_WAIT_L(n) asm volatile("s_waitcnt lgkmcnt(" #n ")" ::: "memory")
; #define PG8_BAR __builtin_amdgcn_s_barrier()
; #define PG8_SCHED __builtin_amdgcn_sched_barrier(0)
; template <class Epi, class Sched, bool ALIGN_EPI = false, bool SP2 = false>
; __device__ __forceinline__ void gemm_phase(PG8_LAS unsigned char* lds, const Gemm g, const Sched& S, const Epi& E) {
;     ...
;             PG8_LDB(B0, 1, 0); PG8_LDB(B1, 1, 1); PG8_SCHED; PG8_LDA(At, 1, 0); PG8_STAGE(PG8_SA(0, 1), a2 + hstep, voffA);
;             PG8_WAIT_V(8); PG8_WAIT_L(0); PG8_BAR; PG8_MMA(0, 0, At, B0); PG8_MMA(0, 1, At, B1); PG8_BAR; PG8_SCHED;
;             PG8_LDA(At, 1, 1); PG8_STAGE(PG8_SB(1, 0), b3, voffB); PG8_STAGE(PG8_SB(1, 1), b3 + hstep, voffB); PG8_STAGE(PG8_SA(1, 0), a3, voffA);
;             PG8_WAIT_V(8); PG8_WAIT_L(0); PG8_BAR; PG8_MMA(1, 0, At, B0); PG8_MMA(1, 1, At, B1); PG8_BAR; PG8_SCHED;
;     ...
;         if constexpr (ALIGN_EPI) { if (wr == 0) PG8_BAR; }
	s_add_i32 s54, 0, 0x18000
	s_add_i32 s55, 0, 0x1c000
	ds_read_b128 v[82:85], v244 offset:32768
	ds_read_b128 v[86:89], v244 offset:33792
	ds_read_b128 v[90:93], v244 offset:34816
	ds_read_b128 v[94:97], v244 offset:35840
	ds_read_b128 v[146:149], v244 offset:49152
	ds_read_b128 v[150:153], v244 offset:50176
	ds_read_b128 v[154:157], v244 offset:51200
	ds_read_b128 v[158:161], v244 offset:52224
	s_add_u32 s14, s22, 0x80000
	s_addc_u32 s15, s23, 0
	s_mov_b32 m0, s29
	ds_read_b128 v[178:181], v188 offset:32768
	ds_read_b128 v[190:193], v188 offset:33792
	ds_read_b128 v[194:197], v188 offset:34816
	ds_read_b128 v[198:201], v188 offset:35840
	ds_read_b128 v[202:205], v188 offset:36864
	ds_read_b128 v[206:209], v188 offset:37888
	ds_read_b128 v[210:213], v188 offset:38912
	ds_read_b128 v[220:223], v188 offset:39936
	s_nop 0
	global_load_lds_dwordx4 v1, s[14:15]
	s_mov_b32 m0, s33
	s_nop 0
	global_load_lds_dwordx4 v164, s[14:15]
	s_waitcnt vmcnt(8)
	s_waitcnt lgkmcnt(0)
	s_barrier
	s_waitcnt lgkmcnt(0)
	v_mfma_f32_16x16x32_bf16 v[142:145], v[82:85], v[178:181], v[142:145]
	v_mfma_f32_16x16x32_bf16 v[142:145], v[86:89], v[190:193], v[142:145]
	v_mfma_f32_16x16x32_bf16 v[126:129], v[82:85], v[194:197], v[126:129]
	v_mfma_f32_16x16x32_bf16 v[126:129], v[86:89], v[198:201], v[126:129]
	v_mfma_f32_16x16x32_bf16 v[110:113], v[82:85], v[202:205], v[110:113]
	v_mfma_f32_16x16x32_bf16 v[110:113], v[86:89], v[206:209], v[110:113]
	v_mfma_f32_16x16x32_bf16 v[78:81], v[82:85], v[210:213], v[78:81]
	v_mfma_f32_16x16x32_bf16 v[78:81], v[86:89], v[220:223], v[78:81]
	v_mfma_f32_16x16x32_bf16 v[138:141], v[90:93], v[178:181], v[138:141]
	v_mfma_f32_16x16x32_bf16 v[138:141], v[94:97], v[190:193], v[138:141]
	v_mfma_f32_16x16x32_bf16 v[122:125], v[90:93], v[194:197], v[122:125]
	v_mfma_f32_16x16x32_bf16 v[122:125], v[94:97], v[198:201], v[122:125]
	v_mfma_f32_16x16x32_bf16 v[106:109], v[90:93], v[202:205], v[106:109]
	v_mfma_f32_16x16x32_bf16 v[106:109], v[94:97], v[206:209], v[106:109]
	v_mfma_f32_16x16x32_bf16 v[74:77], v[90:93], v[210:213], v[74:77]
	v_mfma_f32_16x16x32_bf16 v[74:77], v[94:97], v[220:223], v[74:77]
	v_mfma_f32_16x16x32_bf16 v[134:137], v[146:149], v[178:181], v[134:137]
	v_mfma_f32_16x16x32_bf16 v[134:137], v[150:153], v[190:193], v[134:137]
	v_mfma_f32_16x16x32_bf16 v[118:121], v[146:149], v[194:197], v[118:121]
	v_mfma_f32_16x16x32_bf16 v[118:121], v[150:153], v[198:201], v[118:121]
	v_mfma_f32_16x16x32_bf16 v[102:105], v[146:149], v[202:205], v[102:105]
	v_mfma_f32_16x16x32_bf16 v[102:105], v[150:153], v[206:209], v[102:105]
	v_mfma_f32_16x16x32_bf16 v[70:73], v[146:149], v[210:213], v[70:73]
	v_mfma_f32_16x16x32_bf16 v[70:73], v[150:153], v[220:223], v[70:73]
	v_mfma_f32_16x16x32_bf16 v[130:133], v[154:157], v[178:181], v[130:133]
	v_mfma_f32_16x16x32_bf16 v[130:133], v[158:161], v[190:193], v[130:133]
	v_mfma_f32_16x16x32_bf16 v[114:117], v[154:157], v[194:197], v[114:117]
	v_mfma_f32_16x16x32_bf16 v[114:117], v[158:161], v[198:201], v[114:117]
	v_mfma_f32_16x16x32_bf16 v[98:101], v[154:157], v[202:205], v[98:101]
	v_mfma_f32_16x16x32_bf16 v[98:101], v[158:161], v[206:209], v[98:101]
	v_mfma_f32_16x16x32_bf16 v[66:69], v[154:157], v[210:213], v[66:69]
	v_mfma_f32_16x16x32_bf16 v[66:69], v[158:161], v[220:223], v[66:69]
	s_barrier
	s_add_u32 s14, s20, 0x80
	s_addc_u32 s15, s21, 0
	s_add_i32 s22, s54, s26
	ds_read_b128 v[178:181], v188 offset:49152
	ds_read_b128 v[190:193], v188 offset:50176
	ds_read_b128 v[194:197], v188 offset:51200
	ds_read_b128 v[198:201], v188 offset:52224
	ds_read_b128 v[202:205], v188 offset:53248
	ds_read_b128 v[206:209], v188 offset:54272
	ds_read_b128 v[210:213], v188 offset:55296
	ds_read_b128 v[220:223], v188 offset:56320
	s_mov_b32 m0, s22
	s_nop 0
	global_load_lds_dwordx4 v162, s[14:15]
	s_add_i32 m0, s22, 0x2000
	s_nop 0
	global_load_lds_dwordx4 v184, s[14:15]
	s_add_u32 s14, s20, 0x80080
	s_addc_u32 s15, s21, 0
	s_add_i32 s20, s55, s26
	s_mov_b32 m0, s20
	s_nop 0
	global_load_lds_dwordx4 v162, s[14:15]
	s_add_i32 m0, s20, 0x2000
	s_nop 0
	global_load_lds_dwordx4 v184, s[14:15]
	s_mov_b32 m0, s38
	s_nop 0
	global_load_lds_dwordx4 v1, s[18:19]
	s_mov_b32 m0, s39
	s_nop 0
	global_load_lds_dwordx4 v164, s[18:19]
	s_waitcnt vmcnt(8)
	s_waitcnt lgkmcnt(0)
	s_barrier
	s_waitcnt lgkmcnt(0)
	v_mfma_f32_16x16x32_bf16 v[62:65], v[82:85], v[178:181], v[62:65]
	v_mfma_f32_16x16x32_bf16 v[62:65], v[86:89], v[190:193], v[62:65]
	v_mfma_f32_16x16x32_bf16 v[46:49], v[82:85], v[194:197], v[46:49]
	v_mfma_f32_16x16x32_bf16 v[46:49], v[86:89], v[198:201], v[46:49]
	v_mfma_f32_16x16x32_bf16 v[30:33], v[82:85], v[202:205], v[30:33]
	v_mfma_f32_16x16x32_bf16 v[30:33], v[86:89], v[206:209], v[30:33]
	v_mfma_f32_16x16x32_bf16 v[14:17], v[82:85], v[210:213], v[14:17]
	v_mfma_f32_16x16x32_bf16 v[14:17], v[86:89], v[220:223], v[14:17]
	v_mfma_f32_16x16x32_bf16 v[58:61], v[90:93], v[178:181], v[58:61]
	v_mfma_f32_16x16x32_bf16 v[58:61], v[94:97], v[190:193], v[58:61]
	v_mfma_f32_16x16x32_bf16 v[42:45], v[90:93], v[194:197], v[42:45]
	v_mfma_f32_16x16x32_bf16 v[42:45], v[94:97], v[198:201], v[42:45]
	v_mfma_f32_16x16x32_bf16 v[26:29], v[90:93], v[202:205], v[26:29]
	v_mfma_f32_16x16x32_bf16 v[26:29], v[94:97], v[206:209], v[26:29]
	v_mfma_f32_16x16x32_bf16 v[10:13], v[90:93], v[210:213], v[10:13]
	v_mfma_f32_16x16x32_bf16 v[10:13], v[94:97], v[220:223], v[10:13]
	v_mfma_f32_16x16x32_bf16 v[54:57], v[146:149], v[178:181], v[54:57]
	v_mfma_f32_16x16x32_bf16 v[54:57], v[150:153], v[190:193], v[54:57]
	v_mfma_f32_16x16x32_bf16 v[38:41], v[146:149], v[194:197], v[38:41]
	v_mfma_f32_16x16x32_bf16 v[38:41], v[150:153], v[198:201], v[38:41]
	v_mfma_f32_16x16x32_bf16 v[22:25], v[146:149], v[202:205], v[22:25]
	v_mfma_f32_16x16x32_bf16 v[22:25], v[150:153], v[206:209], v[22:25]
	v_mfma_f32_16x16x32_bf16 v[6:9], v[146:149], v[210:213], v[6:9]
	v_mfma_f32_16x16x32_bf16 v[6:9], v[150:153], v[220:223], v[6:9]
	v_mfma_f32_16x16x32_bf16 v[50:53], v[154:157], v[178:181], v[50:53]
	v_mfma_f32_16x16x32_bf16 v[50:53], v[158:161], v[190:193], v[50:53]
	v_mfma_f32_16x16x32_bf16 v[34:37], v[154:157], v[194:197], v[34:37]
	v_mfma_f32_16x16x32_bf16 v[34:37], v[158:161], v[198:201], v[34:37]
	v_mfma_f32_16x16x32_bf16 v[18:21], v[154:157], v[202:205], v[18:21]
	v_mfma_f32_16x16x32_bf16 v[18:21], v[158:161], v[206:209], v[18:21]
	v_mfma_f32_16x16x32_bf16 v[2:5], v[154:157], v[210:213], v[2:5]
	v_mfma_f32_16x16x32_bf16 v[2:5], v[158:161], v[220:223], v[2:5]
	s_barrier
	s_add_i32 s53, s53, 2
	s_add_u32 s51, s51, 0x100
	s_addc_u32 s52, s52, 0
	s_cmp_gt_u32 s53, 29
	s_mov_b64 s[14:15], s[16:17]
	s_cbranch_scc0 .LBB0_634
	s_and_b64 vcc, exec, s[2:3]
	s_cbranch_vccz .LBB0_637
	s_barrier

; #define PG8_STAGE(bufoff, gbase, voff) do { const char* gb_ = (const char*)(gbase); asm volatile("" : "+s"(gb_)); _Pragma("unroll") for (int _i = 0; _i < 2; ++_i) { unsigned vo_ = (voff)[_i]; asm volatile("" : "+v"(vo_));        \
;         __builtin_amdgcn_global_load_lds((const unsigned*)(gb_ + vo_), (PG8_LAS unsigned*)(lds + (bufoff) + ldsw + _i * 8192), 16, 0, 0); } } while (0)
; #define PG8_LDA(dst, b, h) do { _Pragma("unroll") for (int m = 0; m < 4; ++m) _Pragma("unroll") for (int k = 0; k < 2; ++k) dst[m][k] = *(const PG8_LAS bf16x8*)(lds + PG8_SA(b, h) + aoff + m * 2048 + k * 1024); } while (0)
; #define PG8_LDB(dst, b, h) do { _Pragma("unroll") for (int n = 0; n < 2; ++n) _Pragma("unroll") for (int k = 0; k < 2; ++k) dst[n][k] = *(const PG8_LAS bf16x8*)(lds + PG8_SB(b, h) + boff + n * 2048 + k * 1024); } while (0)
; #define PG8_MMA(ai, bj, At, Bt) do { __builtin_amdgcn_s_setprio(1); _Pragma("unroll") for (int m = 0; m < 4; ++m) _Pragma("unroll") for (int n = 0; n < 2; ++n) _Pragma("unroll") for (int k = 0; k < 2; ++k) \
;         acc[ai][bj][m][n] = __builtin_amdgcn_mfma_f32_16x16x32_bf16(Bt[n][k], At[m][k], acc[ai][bj][m][n], 0, 0, 0); __builtin_amdgcn_s_setprio(0); } while (0)
; template <class Epi, class Sched, bool ALIGN_EPI = false, bool SP2 = false>
; __device__ __forceinline__ void gemm_phase(PG8_LAS unsigned char* lds, const Gemm g, const Sched& S, const Epi& E) {
;     ...
;         for (int t = 0; t < nt; t += 2) {
;             const bool last = (t == nt - 2);
;             const char* a1 = cA + (size_t)(t + 1) * kstep;
;             const char* a2 = last ? nA : cA + (size_t)(t + 2) * kstep; const char* b2 = last ? nB : cB + (size_t)(t + 2) * kstep;
;             const char* a3 = a2 + kstep; const char* b3 = b2 + kstep;
;             if (last && has_next) S.a_ready(nxt);
;             if constexpr (SP2) {
;             PG8_LDB(B0, 0, 0); PG8_LDB(B1, 0, 1); PG8_SCHED; PG8_LDA(At, 0, 0); PG8_STAGE(PG8_SA(1, 1), a1 + hstep, voffA);
;             PG8_WAIT_V(8); PG8_WAIT_L(0); PG8_BAR; PG8_MMA(0, 0, At, B0); PG8_MMA(0, 1, At, B1); PG8_BAR; PG8_SCHED;
;             PG8_LDA(At, 0, 1); PG8_STAGE(PG8_SB(0, 0), b2, voffB); PG8_STAGE(PG8_SB(0, 1), b2 + hstep, voffB); PG8_STAGE(PG8_SA(0, 0), a2, voffA);
;             PG8_WAIT_V(8); PG8_WAIT_L(0); PG8_BAR; PG8_MMA(1, 0, At, B0); PG8_MMA(1, 1, At, B1); PG8_BAR; PG8_SCHED;
.LBB0_707:
	s_add_u32 s2, s4, 0x100
	s_addc_u32 s3, s5, 0
	s_cmpk_eq_i32 s35, 0x54
	s_cselect_b32 s10, s52, s2
	s_cselect_b32 s11, s53, s3
	s_cselect_b32 s8, s42, s31
	s_cselect_b32 s9, s43, s34
	s_add_u32 s6, s10, 0x80
	s_addc_u32 s7, s11, 0
	s_add_i32 s38, 0, 0x10000
	s_add_i32 s39, 0, 0x14000
	ds_read_b128 v[34:37], v244
	ds_read_b128 v[38:41], v244 offset:1024
	ds_read_b128 v[98:101], v244 offset:2048
	ds_read_b128 v[102:105], v244 offset:3072
	ds_read_b128 v[146:149], v244 offset:16384
	ds_read_b128 v[150:153], v244 offset:17408
	ds_read_b128 v[154:157], v244 offset:18432
	ds_read_b128 v[158:161], v244 offset:19456
	s_add_u32 s4, s4, 0x160080
	s_addc_u32 s5, s5, 0
	ds_read_b128 v[178:181], v194
	ds_read_b128 v[182:185], v194 offset:1024
	ds_read_b128 v[186:189], v194 offset:2048
	ds_read_b128 v[196:199], v194 offset:3072
	ds_read_b128 v[200:203], v194 offset:4096
	ds_read_b128 v[204:207], v194 offset:5120
	ds_read_b128 v[208:211], v194 offset:6144
	ds_read_b128 v[212:215], v194 offset:7168
	s_add_i32 m0, s16, 0xc000
	s_nop 0
	global_load_lds_dwordx4 v1, s[4:5]
	s_add_i32 m0, s16, 0xe000
	s_nop 0
	global_load_lds_dwordx4 v164, s[4:5]
	s_waitcnt vmcnt(8)
	s_waitcnt lgkmcnt(0)
	s_barrier
	s_waitcnt lgkmcnt(0)
	v_mfma_f32_16x16x32_bf16 v[142:145], v[34:37], v[178:181], v[142:145]
	v_mfma_f32_16x16x32_bf16 v[142:145], v[38:41], v[182:185], v[142:145]
	v_mfma_f32_16x16x32_bf16 v[134:137], v[34:37], v[186:189], v[134:137]
	v_mfma_f32_16x16x32_bf16 v[134:137], v[38:41], v[196:199], v[134:137]
	v_mfma_f32_16x16x32_bf16 v[126:129], v[34:37], v[200:203], v[126:129]
	v_mfma_f32_16x16x32_bf16 v[126:129], v[38:41], v[204:207], v[126:129]
	v_mfma_f32_16x16x32_bf16 v[118:121], v[34:37], v[208:211], v[118:121]
	v_mfma_f32_16x16x32_bf16 v[118:121], v[38:41], v[212:215], v[118:121]
	v_mfma_f32_16x16x32_bf16 v[138:141], v[98:101], v[178:181], v[138:141]
	v_mfma_f32_16x16x32_bf16 v[138:141], v[102:105], v[182:185], v[138:141]
	v_mfma_f32_16x16x32_bf16 v[130:133], v[98:101], v[186:189], v[130:133]
	v_mfma_f32_16x16x32_bf16 v[130:133], v[102:105], v[196:199], v[130:133]
	v_mfma_f32_16x16x32_bf16 v[122:125], v[98:101], v[200:203], v[122:125]
	v_mfma_f32_16x16x32_bf16 v[122:125], v[102:105], v[204:207], v[122:125]
	v_mfma_f32_16x16x32_bf16 v[114:117], v[98:101], v[208:211], v[114:117]
	v_mfma_f32_16x16x32_bf16 v[114:117], v[102:105], v[212:215], v[114:117]
	v_mfma_f32_16x16x32_bf16 v[70:73], v[146:149], v[178:181], v[70:73]
	v_mfma_f32_16x16x32_bf16 v[70:73], v[150:153], v[182:185], v[70:73]
	v_mfma_f32_16x16x32_bf16 v[62:65], v[146:149], v[186:189], v[62:65]
	v_mfma_f32_16x16x32_bf16 v[62:65], v[150:153], v[196:199], v[62:65]
	v_mfma_f32_16x16x32_bf16 v[54:57], v[146:149], v[200:203], v[54:57]
	v_mfma_f32_16x16x32_bf16 v[54:57], v[150:153], v[204:207], v[54:57]
	v_mfma_f32_16x16x32_bf16 v[46:49], v[146:149], v[208:211], v[46:49]
	v_mfma_f32_16x16x32_bf16 v[46:49], v[150:153], v[212:215], v[46:49]
	v_mfma_f32_16x16x32_bf16 v[66:69], v[154:157], v[178:181], v[66:69]
	v_mfma_f32_16x16x32_bf16 v[66:69], v[158:161], v[182:185], v[66:69]
	v_mfma_f32_16x16x32_bf16 v[58:61], v[154:157], v[186:189], v[58:61]
	v_mfma_f32_16x16x32_bf16 v[58:61], v[158:161], v[196:199], v[58:61]
	v_mfma_f32_16x16x32_bf16 v[50:53], v[154:157], v[200:203], v[50:53]
	v_mfma_f32_16x16x32_bf16 v[50:53], v[158:161], v[204:207], v[50:53]
	v_mfma_f32_16x16x32_bf16 v[42:45], v[154:157], v[208:211], v[42:45]
	v_mfma_f32_16x16x32_bf16 v[42:45], v[158:161], v[212:215], v[42:45]
	s_barrier
	s_mov_b64 s[4:5], s[8:9]
	s_add_i32 s38, s38, s15
	ds_read_b128 v[178:181], v194 offset:16384
	ds_read_b128 v[182:185], v194 offset:17408
	ds_read_b128 v[186:189], v194 offset:18432
	ds_read_b128 v[196:199], v194 offset:19456
	ds_read_b128 v[200:203], v194 offset:20480
	ds_read_b128 v[204:207], v194 offset:21504
	ds_read_b128 v[208:211], v194 offset:22528
	ds_read_b128 v[212:215], v194 offset:23552
	s_mov_b32 m0, s38
	s_nop 0
	global_load_lds_dwordx4 v162, s[4:5]
	s_add_i32 m0, s38, 0x2000
	s_nop 0
	global_load_lds_dwordx4 v190, s[4:5]
	s_add_u32 s4, s8, 0x160000
	s_addc_u32 s5, s9, 0
	s_add_i32 s38, s39, s15
	s_mov_b32 m0, s38
	s_nop 0
	global_load_lds_dwordx4 v162, s[4:5]
	s_add_i32 m0, s38, 0x2000
	s_nop 0
	global_load_lds_dwordx4 v190, s[4:5]
	s_mov_b64 s[4:5], s[10:11]
	s_mov_b32 m0, s16
	s_nop 0
	global_load_lds_dwordx4 v1, s[4:5]
	s_mov_b32 m0, s17
	s_nop 0
	global_load_lds_dwordx4 v164, s[4:5]
	s_waitcnt vmcnt(8)
	s_waitcnt lgkmcnt(0)
	s_barrier
	s_waitcnt lgkmcnt(0)
	v_mfma_f32_16x16x32_bf16 v[110:113], v[34:37], v[178:181], v[110:113]
	v_mfma_f32_16x16x32_bf16 v[110:113], v[38:41], v[182:185], v[110:113]
	v_mfma_f32_16x16x32_bf16 v[94:97], v[34:37], v[186:189], v[94:97]
	v_mfma_f32_16x16x32_bf16 v[94:97], v[38:41], v[196:199], v[94:97]
	v_mfma_f32_16x16x32_bf16 v[86:89], v[34:37], v[200:203], v[86:89]
	v_mfma_f32_16x16x32_bf16 v[86:89], v[38:41], v[204:207], v[86:89]
	v_mfma_f32_16x16x32_bf16 v[34:37], v[34:37], v[208:211], v[78:81]
	v_mfma_f32_16x16x32_bf16 v[34:37], v[38:41], v[212:215], v[34:37]
	v_mfma_f32_16x16x32_bf16 v[106:109], v[98:101], v[178:181], v[106:109]
	v_mfma_f32_16x16x32_bf16 v[106:109], v[102:105], v[182:185], v[106:109]
	v_mfma_f32_16x16x32_bf16 v[90:93], v[98:101], v[186:189], v[90:93]
	v_mfma_f32_16x16x32_bf16 v[90:93], v[102:105], v[196:199], v[90:93]
	v_mfma_f32_16x16x32_bf16 v[82:85], v[98:101], v[200:203], v[82:85]
	v_mfma_f32_16x16x32_bf16 v[82:85], v[102:105], v[204:207], v[82:85]
	v_mfma_f32_16x16x32_bf16 v[38:41], v[98:101], v[208:211], v[74:77]
	v_mfma_f32_16x16x32_bf16 v[38:41], v[102:105], v[212:215], v[38:41]
	v_mfma_f32_16x16x32_bf16 v[30:33], v[146:149], v[178:181], v[30:33]
	v_mfma_f32_16x16x32_bf16 v[30:33], v[150:153], v[182:185], v[30:33]
	v_mfma_f32_16x16x32_bf16 v[22:25], v[146:149], v[186:189], v[22:25]
	v_mfma_f32_16x16x32_bf16 v[22:25], v[150:153], v[196:199], v[22:25]
	v_mfma_f32_16x16x32_bf16 v[14:17], v[146:149], v[200:203], v[14:17]
	v_mfma_f32_16x16x32_bf16 v[14:17], v[150:153], v[204:207], v[14:17]
	v_mfma_f32_16x16x32_bf16 v[6:9], v[146:149], v[208:211], v[6:9]
	v_mfma_f32_16x16x32_bf16 v[6:9], v[150:153], v[212:215], v[6:9]
	v_mfma_f32_16x16x32_bf16 v[26:29], v[154:157], v[178:181], v[26:29]
	v_mfma_f32_16x16x32_bf16 v[26:29], v[158:161], v[182:185], v[26:29]
	v_mfma_f32_16x16x32_bf16 v[18:21], v[154:157], v[186:189], v[18:21]
	v_mfma_f32_16x16x32_bf16 v[18:21], v[158:161], v[196:199], v[18:21]
	v_mfma_f32_16x16x32_bf16 v[10:13], v[154:157], v[200:203], v[10:13]
	v_mfma_f32_16x16x32_bf16 v[10:13], v[158:161], v[204:207], v[10:13]
	v_mfma_f32_16x16x32_bf16 v[2:5], v[154:157], v[208:211], v[2:5]
	v_mfma_f32_16x16x32_bf16 v[2:5], v[158:161], v[212:215], v[2:5]
	s_barrier
; #define PG8_STAGE(bufoff, gbase, voff) do { const char* gb_ = (const char*)(gbase); asm volatile("" : "+s"(gb_)); _Pragma("unroll") for (int _i = 0; _i < 2; ++_i) { unsigned vo_ = (voff)[_i]; asm volatile("" : "+v"(vo_));        \
;         __builtin_amdgcn_global_load_lds((const unsigned*)(gb_ + vo_), (PG8_LAS unsigned*)(lds + (bufoff) + ldsw + _i * 8192), 16, 0, 0); } } while (0)
; #define PG8_LDA(dst, b, h) do { _Pragma("unroll") for (int m = 0; m < 4; ++m) _Pragma("unroll") for (int k = 0; k < 2; ++k) dst[m][k] = *(const PG8_LAS bf16x8*)(lds + PG8_SA(b, h) + aoff + m * 2048 + k * 1024); } while (0)
; #define PG8_LDB(dst, b, h) do { _Pragma("unroll") for (int n = 0; n < 2; ++n) _Pragma("unroll") for (int k = 0; k < 2; ++k) dst[n][k] = *(const PG8_LAS bf16x8*)(lds + PG8_SB(b, h) + boff + n * 2048 + k * 1024); } while (0)
; #define PG8_MMA(ai, bj, At, Bt) do { __builtin_amdgcn_s_setprio(1); _Pragma("unroll") for (int m = 0; m < 4; ++m) _Pragma("unroll") for (int n = 0; n < 2; ++n) _Pragma("unroll") for (int k = 0; k < 2; ++k) \
;         acc[ai][bj][m][n] = __builtin_amdgcn_mfma_f32_16x16x32_bf16(Bt[n][k], At[m][k], acc[ai][bj][m][n], 0, 0, 0); __builtin_amdgcn_s_setprio(0); } while (0)
; #define PG8_WAIT_V(n) asm volatile("s_waitcnt vmcnt(" #n ")" ::: "memory")
; #define PG8_WAIT_L(n) asm volatile("s_waitcnt lgkmcnt(" #n ")" ::: "memory")
; #define PG8_BAR __builtin_amdgcn_s_barrier()
; #define PG8_SCHED __builtin_amdgcn_sched_barrier(0)
; template <class Epi, class Sched, bool ALIGN_EPI = false, bool SP2 = false>
; __device__ __forceinline__ void gemm_phase(PG8_LAS unsigned char* lds, const Gemm g, const Sched& S, const Epi& E) {
;     ...
;             PG8_LDB(B0, 1, 0); PG8_LDB(B1, 1, 1); PG8_SCHED; PG8_LDA(At, 1, 0); PG8_STAGE(PG8_SA(0, 1), a2 + hstep, voffA);
;             PG8_WAIT_V(8); PG8_WAIT_L(0); PG8_BAR; PG8_MMA(0, 0, At, B0); PG8_MMA(0, 1, At, B1); PG8_BAR; PG8_SCHED;
;             PG8_LDA(At, 1, 1); PG8_STAGE(PG8_SB(1, 0), b3, voffB); PG8_STAGE(PG8_SB(1, 1), b3 + hstep, voffB); PG8_STAGE(PG8_SA(1, 0), a3, voffA);
;             PG8_WAIT_V(8); PG8_WAIT_L(0); PG8_BAR; PG8_MMA(1, 0, At, B0); PG8_MMA(1, 1, At, B1); PG8_BAR; PG8_SCHED;
	s_add_i32 s38, 0, 0x18000
	s_add_i32 s39, 0, 0x1c000
	ds_read_b128 v[74:77], v244 offset:32768
	ds_read_b128 v[78:81], v244 offset:33792
	ds_read_b128 v[98:101], v244 offset:34816
	ds_read_b128 v[102:105], v244 offset:35840
	ds_read_b128 v[146:149], v244 offset:49152
	ds_read_b128 v[150:153], v244 offset:50176
	ds_read_b128 v[154:157], v244 offset:51200
	ds_read_b128 v[158:161], v244 offset:52224
	s_add_u32 s4, s10, 0x160000
	s_addc_u32 s5, s11, 0
	s_mov_b32 m0, s18
	ds_read_b128 v[178:181], v194 offset:32768
	ds_read_b128 v[182:185], v194 offset:33792
	ds_read_b128 v[186:189], v194 offset:34816
	ds_read_b128 v[196:199], v194 offset:35840
	ds_read_b128 v[200:203], v194 offset:36864
	ds_read_b128 v[204:207], v194 offset:37888
	ds_read_b128 v[208:211], v194 offset:38912
	ds_read_b128 v[212:215], v194 offset:39936
	s_nop 0
	global_load_lds_dwordx4 v1, s[4:5]
	s_mov_b32 m0, s19
	s_nop 0
	global_load_lds_dwordx4 v164, s[4:5]
	s_waitcnt vmcnt(8)
	s_waitcnt lgkmcnt(0)
	s_barrier
	s_waitcnt lgkmcnt(0)
	v_mfma_f32_16x16x32_bf16 v[142:145], v[74:77], v[178:181], v[142:145]
	v_mfma_f32_16x16x32_bf16 v[142:145], v[78:81], v[182:185], v[142:145]
	v_mfma_f32_16x16x32_bf16 v[134:137], v[74:77], v[186:189], v[134:137]
	v_mfma_f32_16x16x32_bf16 v[134:137], v[78:81], v[196:199], v[134:137]
	v_mfma_f32_16x16x32_bf16 v[126:129], v[74:77], v[200:203], v[126:129]
	v_mfma_f32_16x16x32_bf16 v[126:129], v[78:81], v[204:207], v[126:129]
	v_mfma_f32_16x16x32_bf16 v[118:121], v[74:77], v[208:211], v[118:121]
	v_mfma_f32_16x16x32_bf16 v[118:121], v[78:81], v[212:215], v[118:121]
	v_mfma_f32_16x16x32_bf16 v[138:141], v[98:101], v[178:181], v[138:141]
	v_mfma_f32_16x16x32_bf16 v[138:141], v[102:105], v[182:185], v[138:141]
	v_mfma_f32_16x16x32_bf16 v[130:133], v[98:101], v[186:189], v[130:133]
	v_mfma_f32_16x16x32_bf16 v[130:133], v[102:105], v[196:199], v[130:133]
	v_mfma_f32_16x16x32_bf16 v[122:125], v[98:101], v[200:203], v[122:125]
	v_mfma_f32_16x16x32_bf16 v[122:125], v[102:105], v[204:207], v[122:125]
	v_mfma_f32_16x16x32_bf16 v[114:117], v[98:101], v[208:211], v[114:117]
	v_mfma_f32_16x16x32_bf16 v[114:117], v[102:105], v[212:215], v[114:117]
	v_mfma_f32_16x16x32_bf16 v[70:73], v[146:149], v[178:181], v[70:73]
	v_mfma_f32_16x16x32_bf16 v[70:73], v[150:153], v[182:185], v[70:73]
	v_mfma_f32_16x16x32_bf16 v[62:65], v[146:149], v[186:189], v[62:65]
	v_mfma_f32_16x16x32_bf16 v[62:65], v[150:153], v[196:199], v[62:65]
	v_mfma_f32_16x16x32_bf16 v[54:57], v[146:149], v[200:203], v[54:57]
	v_mfma_f32_16x16x32_bf16 v[54:57], v[150:153], v[204:207], v[54:57]
	v_mfma_f32_16x16x32_bf16 v[46:49], v[146:149], v[208:211], v[46:49]
	v_mfma_f32_16x16x32_bf16 v[46:49], v[150:153], v[212:215], v[46:49]
	v_mfma_f32_16x16x32_bf16 v[66:69], v[154:157], v[178:181], v[66:69]
	v_mfma_f32_16x16x32_bf16 v[66:69], v[158:161], v[182:185], v[66:69]
	v_mfma_f32_16x16x32_bf16 v[58:61], v[154:157], v[186:189], v[58:61]
	v_mfma_f32_16x16x32_bf16 v[58:61], v[158:161], v[196:199], v[58:61]
	v_mfma_f32_16x16x32_bf16 v[50:53], v[154:157], v[200:203], v[50:53]
	v_mfma_f32_16x16x32_bf16 v[50:53], v[158:161], v[204:207], v[50:53]
	v_mfma_f32_16x16x32_bf16 v[42:45], v[154:157], v[208:211], v[42:45]
	v_mfma_f32_16x16x32_bf16 v[42:45], v[158:161], v[212:215], v[42:45]
	s_barrier
	s_add_u32 s4, s8, 0x80
	s_addc_u32 s5, s9, 0
	s_add_i32 s10, s38, s15
	ds_read_b128 v[178:181], v194 offset:49152
	ds_read_b128 v[182:185], v194 offset:50176
	ds_read_b128 v[186:189], v194 offset:51200
	ds_read_b128 v[196:199], v194 offset:52224
	ds_read_b128 v[200:203], v194 offset:53248
	ds_read_b128 v[204:207], v194 offset:54272
	ds_read_b128 v[208:211], v194 offset:55296
	ds_read_b128 v[212:215], v194 offset:56320
	s_mov_b32 m0, s10
	s_nop 0
	global_load_lds_dwordx4 v162, s[4:5]
	s_add_i32 m0, s10, 0x2000
	s_nop 0
	global_load_lds_dwordx4 v190, s[4:5]
	s_add_u32 s4, s8, 0x160080
	s_addc_u32 s5, s9, 0
	s_add_i32 s8, s39, s15
	s_mov_b32 m0, s8
	s_nop 0
	global_load_lds_dwordx4 v162, s[4:5]
	s_add_i32 m0, s8, 0x2000
	s_nop 0
	global_load_lds_dwordx4 v190, s[4:5]
	s_mov_b32 m0, s24
	s_nop 0
	global_load_lds_dwordx4 v1, s[6:7]
	s_mov_b32 m0, s25
	s_nop 0
	global_load_lds_dwordx4 v164, s[6:7]
	s_waitcnt vmcnt(8)
	s_waitcnt lgkmcnt(0)
	s_barrier
; #define PG8_STAGE(bufoff, gbase, voff) do { const char* gb_ = (const char*)(gbase); asm volatile("" : "+s"(gb_)); _Pragma("unroll") for (int _i = 0; _i < 2; ++_i) { unsigned vo_ = (voff)[_i]; asm volatile("" : "+v"(vo_));        \
;         __builtin_amdgcn_global_load_lds((const unsigned*)(gb_ + vo_), (PG8_LAS unsigned*)(lds + (bufoff) + ldsw + _i * 8192), 16, 0, 0); } } while (0)
; #define PG8_LDA(dst, b, h) do { _Pragma("unroll") for (int m = 0; m < 4; ++m) _Pragma("unroll") for (int k = 0; k < 2; ++k) dst[m][k] = *(const PG8_LAS bf16x8*)(lds + PG8_SA(b, h) + aoff + m * 2048 + k * 1024); } while (0)
; #define PG8_WAIT_V(n) asm volatile("s_waitcnt vmcnt(" #n ")" ::: "memory")
; #define PG8_WAIT_L(n) asm volatile("s_waitcnt lgkmcnt(" #n ")" ::: "memory")
; #define PG8_BAR __builtin_amdgcn_s_barrier()
; #define PG8_SCHED __builtin_amdgcn_sched_barrier(0)
;     __device__ __forceinline__ void operator()(const f32x4 (&acc)[2][2][4][2], const Unit& u, int wr, int wc, int fr, int fq) const {
;         const int row0 = u.pm * BM + wr * 64 + fr, col0 = u.pn * BM + wc * 32 + 8 * fq, b = (u.pm * BM) / rows_per_batch;
;         const float* g = gate + (size_t)b * gate_bstride + col0;
;         float ssq[2][4];
; #pragma unroll
;         for (int ai = 0; ai < 2; ++ai)
; #pragma unroll
;             for (int m = 0; m < 4; ++m) ssq[ai][m] = 0.f;
;         f32x4 gv[2][2], Gv[2][2];
; #pragma unroll
;         for (int bj = 0; bj < 2; ++bj) { gv[bj][0] = *(const f32x4*)(g + bj * HALF); gv[bj][1] = *(const f32x4*)(g + bj * HALF + 4); Gv[bj][0] = (f32x4){0.f, 0.f, 0.f, 0.f}; Gv[bj][1] = (f32x4){0.f, 0.f, 0.f, 0.f};
;             if (Hn) { const float* sc = scnext + (size_t)b * gate_bstride + col0 + bj * HALF;
;                 Gv[bj][0] = *(const f32x4*)(gnext + col0 + bj * HALF) * (1.0f + *(const f32x4*)(sc)); Gv[bj][1] = *(const f32x4*)(gnext + col0 + bj * HALF + 4) * (1.0f + *(const f32x4*)(sc + 4)); } }
; template <class Epi, class Sched, bool ALIGN_EPI = false, bool SP2 = false>
; __device__ __forceinline__ void gemm_phase(PG8_LAS unsigned char* lds, const Gemm g, const Sched& S, const Epi& E) {
;     ...
;             PG8_LDA(At, 1, 1); PG8_STAGE(PG8_SB(1, 0), b3, voffB); PG8_STAGE(PG8_SB(1, 1), b3 + hstep, voffB); PG8_STAGE(PG8_SA(1, 0), a3, voffA);
;             PG8_WAIT_V(8); PG8_WAIT_L(0); PG8_BAR; PG8_MMA(1, 0, At, B0); PG8_MMA(1, 1, At, B1); PG8_BAR; PG8_SCHED;
	s_waitcnt lgkmcnt(0)
	v_mfma_f32_16x16x32_bf16 v[110:113], v[74:77], v[178:181], v[110:113]
	v_mfma_f32_16x16x32_bf16 v[110:113], v[78:81], v[182:185], v[110:113]
	v_mfma_f32_16x16x32_bf16 v[94:97], v[74:77], v[186:189], v[94:97]
	v_mfma_f32_16x16x32_bf16 v[94:97], v[78:81], v[196:199], v[94:97]
	v_mfma_f32_16x16x32_bf16 v[86:89], v[74:77], v[200:203], v[86:89]
	v_mfma_f32_16x16x32_bf16 v[86:89], v[78:81], v[204:207], v[86:89]
	v_mfma_f32_16x16x32_bf16 v[34:37], v[74:77], v[208:211], v[34:37]
	v_mfma_f32_16x16x32_bf16 v[78:81], v[78:81], v[212:215], v[34:37]
	v_mfma_f32_16x16x32_bf16 v[106:109], v[98:101], v[178:181], v[106:109]
	v_mfma_f32_16x16x32_bf16 v[106:109], v[102:105], v[182:185], v[106:109]
	v_mfma_f32_16x16x32_bf16 v[90:93], v[98:101], v[186:189], v[90:93]
	v_mfma_f32_16x16x32_bf16 v[90:93], v[102:105], v[196:199], v[90:93]
	v_mfma_f32_16x16x32_bf16 v[82:85], v[98:101], v[200:203], v[82:85]
	v_mfma_f32_16x16x32_bf16 v[82:85], v[102:105], v[204:207], v[82:85]
	v_mfma_f32_16x16x32_bf16 v[34:37], v[98:101], v[208:211], v[38:41]
	v_mfma_f32_16x16x32_bf16 v[74:77], v[102:105], v[212:215], v[34:37]
	v_mfma_f32_16x16x32_bf16 v[30:33], v[146:149], v[178:181], v[30:33]
	v_mfma_f32_16x16x32_bf16 v[30:33], v[150:153], v[182:185], v[30:33]
	v_mfma_f32_16x16x32_bf16 v[22:25], v[146:149], v[186:189], v[22:25]
	v_mfma_f32_16x16x32_bf16 v[22:25], v[150:153], v[196:199], v[22:25]
	v_mfma_f32_16x16x32_bf16 v[14:17], v[146:149], v[200:203], v[14:17]
	v_mfma_f32_16x16x32_bf16 v[14:17], v[150:153], v[204:207], v[14:17]
	v_mfma_f32_16x16x32_bf16 v[6:9], v[146:149], v[208:211], v[6:9]
	v_mfma_f32_16x16x32_bf16 v[6:9], v[150:153], v[212:215], v[6:9]
	v_mfma_f32_16x16x32_bf16 v[26:29], v[154:157], v[178:181], v[26:29]
	v_mfma_f32_16x16x32_bf16 v[26:29], v[158:161], v[182:185], v[26:29]
	v_mfma_f32_16x16x32_bf16 v[18:21], v[154:157], v[186:189], v[18:21]
	v_mfma_f32_16x16x32_bf16 v[18:21], v[158:161], v[196:199], v[18:21]
	v_mfma_f32_16x16x32_bf16 v[10:13], v[154:157], v[200:203], v[10:13]
	v_mfma_f32_16x16x32_bf16 v[10:13], v[158:161], v[204:207], v[10:13]
	v_mfma_f32_16x16x32_bf16 v[2:5], v[154:157], v[208:211], v[2:5]
	v_mfma_f32_16x16x32_bf16 v[2:5], v[158:161], v[212:215], v[2:5]
	s_barrier
	s_add_i32 s35, s35, 2
	s_add_u32 s31, s31, 0x100
	s_addc_u32 s34, s34, 0
	s_cmpk_gt_u32 s35, 0x55
	s_mov_b64 s[4:5], s[2:3]
	s_cbranch_scc0 .LBB0_707
	s_ashr_i32 s2, s29, 31
	s_lshr_b32 s2, s2, 27
	s_add_i32 s2, s29, s2
	s_ashr_i32 s2, s2, 5
	v_lshl_or_b32 v156, s30, 8, v193
	s_mul_i32 s5, s2, 0xc000
	v_ashrrev_i32_e32 v157, 31, v156
	s_mul_hi_i32 s4, s2, 0xc000
	s_add_u32 s2, s20, s5
	s_addc_u32 s3, s21, s4
	v_lshlrev_b64 v[34:35], 2, v[156:157]
	v_lshl_add_u64 v[38:39], s[2:3], 0, v[34:35]
	global_load_dwordx4 v[98:101], v[38:39], off offset:16
	global_load_dwordx4 v[102:105], v[38:39], off
	s_add_u32 s2, s22, s5
	s_addc_u32 s3, s23, s4
	v_lshl_add_u64 v[148:149], s[2:3], 0, v[34:35]
	v_lshl_add_u64 v[146:147], s[48:49], 0, v[34:35]
	v_mov_b32_e32 v158, 0
	v_cndmask_b32_e64 v34, 0, 1, s[46:47]
	v_cmp_ne_u32_e64 s[2:3], 1, v34
	s_andn2_b64 vcc, exec, s[46:47]
	v_mov_b32_e32 v159, v158
	v_mov_b32_e32 v160, v158
	v_mov_b32_e32 v161, v158
	v_mov_b32_e32 v178, v158
	v_mov_b32_e32 v179, v158
	v_mov_b32_e32 v180, v158
	v_mov_b32_e32 v181, v158
	s_cbranch_vccnz .LBB0_710
	global_load_dwordx4 v[34:37], v[148:149], off
	global_load_dwordx4 v[150:153], v[148:149], off offset:16
	global_load_dwordx4 v[158:161], v[146:147], off
	global_load_dwordx4 v[178:181], v[146:147], off offset:16
	s_waitcnt vmcnt(0)
	v_pk_add_f32 v[36:37], v[36:37], 1.0 op_sel_hi:[1,0]
	v_pk_add_f32 v[34:35], v[34:35], 1.0 op_sel_hi:[1,0]
	v_pk_add_f32 v[40:41], v[152:153], 1.0 op_sel_hi:[1,0]
	v_pk_add_f32 v[150:151], v[150:151], 1.0 op_sel_hi:[1,0]
	v_pk_mul_f32 v[160:161], v[160:161], v[36:37]
	v_pk_mul_f32 v[158:159], v[158:159], v[34:35]
	v_pk_mul_f32 v[180:181], v[180:181], v[40:41]
	v_pk_mul_f32 v[178:179], v[178:179], v[150:151]
